# v19 plus K step 1 DMA issued in the tile prologue (merge, out, pqr GEMMs) so the two cold misses overlap
# baseline (speedup 1.0000x reference)
.LBB0_311:
	s_lshl_b32 s18, s40, 3
	s_and_b32 s18, s18, 56
	s_bfe_u32 s19, s40, 0x30003
	s_or_b32 s19, s18, s19
	s_lshl_b32 s18, s40, 2
	s_lshr_b32 s24, s40, 3
	s_and_b32 s18, s18, 0xffffff00
	s_lshl_b32 s43, s19, 18
	s_lshl_b32 s19, s19, 19
	s_add_u32 s25, s26, s19
	s_addc_u32 s41, s27, 0
	s_ashr_i32 s19, s18, 31
	s_lshl_b64 s[20:21], s[18:19], 9
	s_lshl_b64 s[18:19], s[18:19], 10
	s_add_u32 s42, s28, s18
	v_readfirstlane_b32 s18, v146
	s_addc_u32 s44, s29, s19
	s_ashr_i32 s45, s18, 6
	s_lshl_b32 s18, s45, 5
	s_ashr_i32 s19, s18, 31
	s_lshl_b64 s[22:23], s[18:19], 11
	s_add_u32 s22, s25, s22
	s_addc_u32 s23, s41, s23
	s_lshl_b64 s[18:19], s[18:19], 10
	s_add_u32 s18, s42, s18
	s_addc_u32 s19, s44, s19
	s_lshl_b32 s25, s45, 12
	s_add_i32 s41, s25, 0x8000
	s_add_u32 s44, s22, 0x4000
	s_barrier
	s_mov_b32 m0, s25
	global_load_lds_dwordx4 v147, s[22:23]
	s_addc_u32 s45, s23, 0
	s_or_b32 s42, s25, 0x400
	s_mov_b32 m0, s42
	global_load_lds_dwordx4 v148, s[44:45]
	s_add_u32 s44, s22, 0x8000
	s_addc_u32 s45, s23, 0
	s_or_b32 s42, s25, 0x800
	s_mov_b32 m0, s42
	global_load_lds_dwordx4 v147, s[44:45]
	s_add_u32 s44, s22, 0xc000
	s_addc_u32 s45, s23, 0
	s_or_b32 s42, s25, 0xc00
	s_mov_b32 m0, s42
	global_load_lds_dwordx4 v148, s[44:45]
	s_add_u32 s44, s18, 0x2000
	s_mov_b32 m0, s41
	global_load_lds_dwordx4 v149, s[18:19]
	s_addc_u32 s45, s19, 0
	s_add_i32 s41, s25, 0x8400
	s_mov_b32 m0, s41
	global_load_lds_dwordx4 v150, s[44:45]
	s_add_u32 s44, s18, 0x4000
	s_addc_u32 s45, s19, 0
	s_add_i32 s41, s25, 0x8800
	s_mov_b32 m0, s41
	global_load_lds_dwordx4 v149, s[44:45]
	s_add_u32 s44, s18, 0x6000
	s_addc_u32 s45, s19, 0
	s_add_i32 s41, s25, 0x8c00
	s_mov_b32 m0, s41
	global_load_lds_dwordx4 v150, s[44:45]
	s_add_u32 s41, s18, 0x6080
	s_addc_u32 s42, s19, 0
	s_add_u32 s44, s18, 0x4080
	s_addc_u32 s45, s19, 0
	s_add_u32 s46, s18, 0x2080
	s_addc_u32 s47, s19, 0
	s_add_u32 s48, s18, 0x80
	s_addc_u32 s49, s19, 0
	s_add_u32 s50, s22, 0xc080
	s_addc_u32 s51, s23, 0
	s_add_u32 s52, s22, 0x8080
	s_addc_u32 s53, s23, 0
	s_add_u32 s54, s22, 0x4080
	s_addc_u32 s55, s23, 0
	s_add_u32 s56, s22, 0x80
	s_addc_u32 s57, s23, 0
	s_mov_b64 s[18:19], 0
	s_mov_b32 s59, 0
	s_mov_b32 s58, 0
	v_mov_b32_e32 v0, 0
	v_mov_b32_e32 v1, v129
	v_mov_b32_e32 v2, v129
	v_mov_b32_e32 v3, v129
	v_mov_b32_e32 v4, v129
	v_mov_b32_e32 v5, v129
	v_mov_b32_e32 v6, v129
	v_mov_b32_e32 v7, v129
	v_mov_b32_e32 v8, v129
	v_mov_b32_e32 v9, v129
	v_mov_b32_e32 v10, v129
	v_mov_b32_e32 v11, v129
	v_mov_b32_e32 v12, v129
	v_mov_b32_e32 v13, v129
	v_mov_b32_e32 v14, v129
	v_mov_b32_e32 v15, v129
	v_mov_b32_e32 v16, 0
	v_mov_b32_e32 v17, v129
	v_mov_b32_e32 v18, v129
	v_mov_b32_e32 v19, v129
	v_mov_b32_e32 v20, v129
	v_mov_b32_e32 v21, v129
	v_mov_b32_e32 v22, v129
	v_mov_b32_e32 v23, v129
	v_mov_b32_e32 v24, v129
	v_mov_b32_e32 v25, v129
	v_mov_b32_e32 v26, v129
	v_mov_b32_e32 v27, v129
	v_mov_b32_e32 v28, v129
	v_mov_b32_e32 v29, v129
	v_mov_b32_e32 v30, v129
	v_mov_b32_e32 v31, v129
	v_mov_b32_e32 v32, 0
	v_mov_b32_e32 v33, v129
	v_mov_b32_e32 v34, v129
	v_mov_b32_e32 v35, v129
	v_mov_b32_e32 v36, v129
	v_mov_b32_e32 v37, v129
	v_mov_b32_e32 v38, v129
	v_mov_b32_e32 v39, v129
	v_mov_b32_e32 v40, v129
	v_mov_b32_e32 v41, v129
	v_mov_b32_e32 v42, v129
	v_mov_b32_e32 v43, v129
	v_mov_b32_e32 v44, v129
	v_mov_b32_e32 v45, v129
	v_mov_b32_e32 v46, v129
	v_mov_b32_e32 v47, v129
	v_mov_b32_e32 v48, 0
	v_mov_b32_e32 v49, v129
	v_mov_b32_e32 v50, v129
	v_mov_b32_e32 v51, v129
	v_mov_b32_e32 v52, v129
	v_mov_b32_e32 v53, v129
	v_mov_b32_e32 v54, v129
	v_mov_b32_e32 v55, v129
	v_mov_b32_e32 v56, v129
	v_mov_b32_e32 v57, v129
	v_mov_b32_e32 v58, v129
	v_mov_b32_e32 v59, v129
	v_mov_b32_e32 v60, v129
	v_mov_b32_e32 v61, v129
	v_mov_b32_e32 v62, v129
	v_mov_b32_e32 v63, v129
	v_mov_b32_e32 v64, 0
	v_mov_b32_e32 v65, v129
	v_mov_b32_e32 v66, v129
	v_mov_b32_e32 v67, v129
	v_mov_b32_e32 v68, v129
	v_mov_b32_e32 v69, v129
	v_mov_b32_e32 v70, v129
	v_mov_b32_e32 v71, v129
	v_mov_b32_e32 v72, v129
	v_mov_b32_e32 v73, v129
	v_mov_b32_e32 v74, v129
	v_mov_b32_e32 v75, v129
	v_mov_b32_e32 v76, v129
	v_mov_b32_e32 v77, v129
	v_mov_b32_e32 v78, v129
	v_mov_b32_e32 v79, v129
	v_mov_b32_e32 v80, 0
	v_mov_b32_e32 v81, v129
	v_mov_b32_e32 v82, v129
	v_mov_b32_e32 v83, v129
	v_mov_b32_e32 v84, v129
	v_mov_b32_e32 v85, v129
	v_mov_b32_e32 v86, v129
	v_mov_b32_e32 v87, v129
	v_mov_b32_e32 v88, v129
	v_mov_b32_e32 v89, v129
	v_mov_b32_e32 v90, v129
	v_mov_b32_e32 v91, v129
	v_mov_b32_e32 v92, v129
	v_mov_b32_e32 v93, v129
	v_mov_b32_e32 v94, v129
	v_mov_b32_e32 v95, v129
	v_mov_b32_e32 v96, 0
	v_mov_b32_e32 v97, v129
	v_mov_b32_e32 v98, v129
	v_mov_b32_e32 v99, v129
	v_mov_b32_e32 v100, v129
	v_mov_b32_e32 v101, v129
	v_mov_b32_e32 v102, v129
	v_mov_b32_e32 v103, v129
	v_mov_b32_e32 v104, v129
	v_mov_b32_e32 v105, v129
	v_mov_b32_e32 v106, v129
	v_mov_b32_e32 v107, v129
	v_mov_b32_e32 v108, v129
	v_mov_b32_e32 v109, v129
	v_mov_b32_e32 v110, v129
	v_mov_b32_e32 v111, v129
	v_mov_b32_e32 v112, 0
	v_mov_b32_e32 v113, v129
	v_mov_b32_e32 v114, v129
	v_mov_b32_e32 v115, v129
	v_mov_b32_e32 v116, v129
	v_mov_b32_e32 v117, v129
	v_mov_b32_e32 v118, v129
	v_mov_b32_e32 v119, v129
	v_mov_b32_e32 v120, v129
	v_mov_b32_e32 v121, v129
	v_mov_b32_e32 v122, v129
	v_mov_b32_e32 v123, v129
	v_mov_b32_e32 v124, v129
	v_mov_b32_e32 v125, v129
	v_mov_b32_e32 v126, v129
	v_mov_b32_e32 v127, v129
	s_add_i32 s60, s59, 0x10000
	s_and_b32 s22, s60, 0x10000
	s_add_i32 s61, s22, s25
	s_add_i32 s62, s61, 0x8000
	s_add_u32 s22, s56, s18
	s_addc_u32 s23, s57, s19
	s_mov_b32 m0, s61
	global_load_lds_dwordx4 v147, s[22:23]
	s_add_u32 s22, s54, s18
	s_addc_u32 s23, s55, s19
	s_add_i32 s63, s61, 0x400
	s_mov_b32 m0, s63
	global_load_lds_dwordx4 v148, s[22:23]
	s_add_u32 s22, s52, s18
	s_addc_u32 s23, s53, s19
	s_add_i32 s63, s61, 0x800
	s_mov_b32 m0, s63
	global_load_lds_dwordx4 v147, s[22:23]
	s_add_u32 s22, s50, s18
	s_addc_u32 s23, s51, s19
	s_add_i32 s63, s61, 0xc00
	s_mov_b32 m0, s63
	global_load_lds_dwordx4 v148, s[22:23]
	s_add_u32 s22, s48, s18
	s_addc_u32 s23, s49, s19
	s_mov_b32 m0, s62
	global_load_lds_dwordx4 v149, s[22:23]
	s_add_u32 s22, s46, s18
	s_addc_u32 s23, s47, s19
	s_add_i32 s62, s61, 0x8400
	s_mov_b32 m0, s62
	global_load_lds_dwordx4 v150, s[22:23]
	s_add_u32 s22, s44, s18
	s_addc_u32 s23, s45, s19
	s_add_i32 s62, s61, 0x8800
	s_mov_b32 m0, s62
	global_load_lds_dwordx4 v149, s[22:23]
	s_add_u32 s22, s41, s18
	s_addc_u32 s23, s42, s19
	s_add_i32 s61, s61, 0x8c00
	s_mov_b32 m0, s61
	global_load_lds_dwordx4 v150, s[22:23]
	s_branch .LBB0_313

.LBB0_313:
	s_waitcnt vmcnt(0)
	s_barrier
	s_and_b32 s22, s59, 0x10000
	v_or_b32_e32 v128, s22, v152
	v_add_u32_e32 v157, v128, v153
	ds_read_b128 v[130:133], v157 offset:32768
	ds_read_b128 v[162:165], v157 offset:36864
	v_add_u32_e32 v180, s22, v151
	v_add_u32_e32 v158, v180, v153
	ds_read_b128 v[134:137], v158
	ds_read_b128 v[138:141], v158 offset:4096
	ds_read_b128 v[142:145], v158 offset:8192
	v_add_u32_e32 v157, v180, v154
	ds_read_b128 v[158:161], v158 offset:12288
	s_sub_u32 s101, s58, 1
	s_cmp_lt_u32 s101, 6
	s_mov_b64 s[22:23], -1
	s_cbranch_scc1 .LBB0_315
	s_add_i32 s60, s59, 0x10000
	s_mov_b64 s[22:23], 0

.LBB0_323:
	v_add_u32_e32 v176, s24, v174
	ds_read_b128 v[186:189], v176
	ds_read_b128 v[190:193], v176 offset:16
	s_add_i32 s24, s24, 0x8200
	s_cmp_lg_u32 s24, 0x20a00
	s_waitcnt vmcnt(3)
	v_lshlrev_b32_e32 v176, 16, v198
	v_and_b32_e32 v177, 0xffff0000, v198
	v_lshlrev_b32_e32 v142, 16, v199
	v_and_b32_e32 v143, 0xffff0000, v199
	v_lshlrev_b32_e32 v180, 16, v200
	v_and_b32_e32 v181, 0xffff0000, v200
	v_lshlrev_b32_e32 v144, 16, v201
	v_and_b32_e32 v145, 0xffff0000, v201
	s_waitcnt lgkmcnt(1)
	v_pk_mul_f32 v[176:177], v[186:187], v[176:177]
	v_pk_mul_f32 v[186:187], v[188:189], v[142:143]
	s_waitcnt lgkmcnt(0)
	v_pk_mul_f32 v[180:181], v[190:191], v[180:181]
	v_pk_mul_f32 v[188:189], v[192:193], v[144:145]
	v_cvt_pk_bf16_f32 v142, v176, v177
	v_cvt_pk_bf16_f32 v143, v186, v187
	v_cvt_pk_bf16_f32 v144, v180, v181
	v_cvt_pk_bf16_f32 v145, v188, v189
	global_store_dwordx4 v[140:141], v[142:145], off offset:-8
	v_lshl_add_u64 v[140:141], v[140:141], 0, s[16:17]
	v_add_u32_e32 v176, s24, v174
	ds_read_b128 v[186:189], v176
	ds_read_b128 v[190:193], v176 offset:16
	s_add_i32 s24, s24, 0x8200
	s_cmp_lg_u32 s24, 0x20a00
	s_waitcnt vmcnt(3)
	v_lshlrev_b32_e32 v176, 16, v202
	v_and_b32_e32 v177, 0xffff0000, v202
	v_lshlrev_b32_e32 v142, 16, v203
	v_and_b32_e32 v143, 0xffff0000, v203
	v_lshlrev_b32_e32 v180, 16, v204
	v_and_b32_e32 v181, 0xffff0000, v204
	v_lshlrev_b32_e32 v144, 16, v205
	v_and_b32_e32 v145, 0xffff0000, v205
	s_waitcnt lgkmcnt(1)
	v_pk_mul_f32 v[176:177], v[186:187], v[176:177]
	v_pk_mul_f32 v[186:187], v[188:189], v[142:143]
	s_waitcnt lgkmcnt(0)
	v_pk_mul_f32 v[180:181], v[190:191], v[180:181]
	v_pk_mul_f32 v[188:189], v[192:193], v[144:145]
	v_cvt_pk_bf16_f32 v142, v176, v177
	v_cvt_pk_bf16_f32 v143, v186, v187
	v_cvt_pk_bf16_f32 v144, v180, v181
	v_cvt_pk_bf16_f32 v145, v188, v189
	global_store_dwordx4 v[140:141], v[142:145], off offset:-8
	v_lshl_add_u64 v[140:141], v[140:141], 0, s[16:17]
	v_add_u32_e32 v176, s24, v174
	ds_read_b128 v[186:189], v176
	ds_read_b128 v[190:193], v176 offset:16
	s_add_i32 s24, s24, 0x8200
	s_cmp_lg_u32 s24, 0x20a00
	s_waitcnt vmcnt(3)
	v_lshlrev_b32_e32 v176, 16, v206
	v_and_b32_e32 v177, 0xffff0000, v206
	v_lshlrev_b32_e32 v142, 16, v207
	v_and_b32_e32 v143, 0xffff0000, v207
	v_lshlrev_b32_e32 v180, 16, v208
	v_and_b32_e32 v181, 0xffff0000, v208
	v_lshlrev_b32_e32 v144, 16, v209
	v_and_b32_e32 v145, 0xffff0000, v209
	s_waitcnt lgkmcnt(1)
	v_pk_mul_f32 v[176:177], v[186:187], v[176:177]
	v_pk_mul_f32 v[186:187], v[188:189], v[142:143]
	s_waitcnt lgkmcnt(0)
	v_pk_mul_f32 v[180:181], v[190:191], v[180:181]
	v_pk_mul_f32 v[188:189], v[192:193], v[144:145]
	v_cvt_pk_bf16_f32 v142, v176, v177
	v_cvt_pk_bf16_f32 v143, v186, v187
	v_cvt_pk_bf16_f32 v144, v180, v181
	v_cvt_pk_bf16_f32 v145, v188, v189
	global_store_dwordx4 v[140:141], v[142:145], off offset:-8
	v_lshl_add_u64 v[140:141], v[140:141], 0, s[16:17]
	v_add_u32_e32 v176, s24, v174
	ds_read_b128 v[186:189], v176
	ds_read_b128 v[190:193], v176 offset:16
	s_add_i32 s24, s24, 0x8200
	s_cmp_lg_u32 s24, 0x20a00
	s_waitcnt vmcnt(3)
	v_lshlrev_b32_e32 v176, 16, v210
	v_and_b32_e32 v177, 0xffff0000, v210
	v_lshlrev_b32_e32 v142, 16, v211
	v_and_b32_e32 v143, 0xffff0000, v211
	v_lshlrev_b32_e32 v180, 16, v212
	v_and_b32_e32 v181, 0xffff0000, v212
	v_lshlrev_b32_e32 v144, 16, v213
	v_and_b32_e32 v145, 0xffff0000, v213
	s_waitcnt lgkmcnt(1)
	v_pk_mul_f32 v[176:177], v[186:187], v[176:177]
	v_pk_mul_f32 v[186:187], v[188:189], v[142:143]
	s_waitcnt lgkmcnt(0)
	v_pk_mul_f32 v[180:181], v[190:191], v[180:181]
	v_pk_mul_f32 v[188:189], v[192:193], v[144:145]
	v_cvt_pk_bf16_f32 v142, v176, v177
	v_cvt_pk_bf16_f32 v143, v186, v187
	v_cvt_pk_bf16_f32 v144, v180, v181
	v_cvt_pk_bf16_f32 v145, v188, v189
	global_store_dwordx4 v[140:141], v[142:145], off offset:-8
	v_lshl_add_u64 v[140:141], v[140:141], 0, s[16:17]
	s_mov_b32 s44, 1
	s_andn2_b64 vcc, exec, s[22:23]
	s_mov_b64 s[22:23], 0
	s_cbranch_vccnz .LBB0_318
	s_lshl_b32 s22, s43, 1
	s_add_u32 s24, s33, s22
	s_addc_u32 s25, s34, 0
	s_lshl_b64 s[20:21], s[20:21], 1
	s_add_u32 s43, s30, s20
	v_readfirstlane_b32 s20, v146
	s_addc_u32 s44, s31, s21
	s_ashr_i32 s45, s20, 6
	s_lshl_b32 s20, s45, 5
	s_ashr_i32 s21, s20, 31
	s_lshl_b64 s[22:23], s[20:21], 11
	s_add_u32 s22, s24, s22
	s_addc_u32 s23, s25, s23
	s_lshl_b64 s[20:21], s[20:21], 10
	s_add_u32 s20, s43, s20
	s_addc_u32 s21, s44, s21
	s_lshl_b32 s24, s45, 12
	s_add_i32 s25, s24, 0x8000
	s_add_u32 s44, s22, 0x4000
	s_barrier
	s_mov_b32 m0, s24
	global_load_lds_dwordx4 v147, s[22:23]
	s_addc_u32 s45, s23, 0
	s_or_b32 s43, s24, 0x400
	s_mov_b32 m0, s43
	global_load_lds_dwordx4 v148, s[44:45]
	s_add_u32 s44, s22, 0x8000
	s_addc_u32 s45, s23, 0
	s_or_b32 s43, s24, 0x800
	s_mov_b32 m0, s43
	global_load_lds_dwordx4 v147, s[44:45]
	s_add_u32 s44, s22, 0xc000
	s_addc_u32 s45, s23, 0
	s_or_b32 s43, s24, 0xc00
	s_mov_b32 m0, s43
	global_load_lds_dwordx4 v148, s[44:45]
	s_add_u32 s44, s20, 0x2000
	s_mov_b32 m0, s25
	global_load_lds_dwordx4 v149, s[20:21]
	s_addc_u32 s45, s21, 0
	s_add_i32 s25, s24, 0x8400
	s_mov_b32 m0, s25
	global_load_lds_dwordx4 v150, s[44:45]
	s_add_u32 s44, s20, 0x4000
	s_addc_u32 s45, s21, 0
	s_add_i32 s25, s24, 0x8800
	s_mov_b32 m0, s25
	global_load_lds_dwordx4 v149, s[44:45]
	s_add_u32 s44, s20, 0x6000
	s_addc_u32 s45, s21, 0
	s_add_i32 s25, s24, 0x8c00
	s_mov_b32 m0, s25
	global_load_lds_dwordx4 v150, s[44:45]
	s_add_u32 s25, s20, 0x6080
	s_addc_u32 s43, s21, 0
	s_add_u32 s44, s20, 0x4080
	s_addc_u32 s45, s21, 0
	s_add_u32 s46, s20, 0x2080
	s_addc_u32 s47, s21, 0
	s_add_u32 s48, s20, 0x80
	s_addc_u32 s49, s21, 0
	s_add_u32 s50, s22, 0xc080
	s_addc_u32 s51, s23, 0
	s_add_u32 s52, s22, 0x8080
	s_addc_u32 s53, s23, 0
	s_add_u32 s54, s22, 0x4080
	s_addc_u32 s55, s23, 0
	s_add_u32 s56, s22, 0x80
	v_mov_b32_e32 v0, 0
	s_addc_u32 s57, s23, 0
	s_mov_b32 s59, 0
	s_mov_b64 s[20:21], 0
	s_mov_b32 s58, 0
	v_mov_b32_e32 v1, v0
	v_mov_b32_e32 v2, v0
	v_mov_b32_e32 v3, v0
	v_mov_b32_e32 v4, v0
	v_mov_b32_e32 v5, v0
	v_mov_b32_e32 v6, v0
	v_mov_b32_e32 v7, v0
	v_mov_b32_e32 v8, v0
	v_mov_b32_e32 v9, v0
	v_mov_b32_e32 v10, v0
	v_mov_b32_e32 v11, v0
	v_mov_b32_e32 v12, v0
	v_mov_b32_e32 v13, v0
	v_mov_b32_e32 v14, v0
	v_mov_b32_e32 v15, v0
	v_mov_b32_e32 v16, v0
	v_mov_b32_e32 v17, v0
	v_mov_b32_e32 v18, v0
	v_mov_b32_e32 v19, v0
	v_mov_b32_e32 v20, v0
	v_mov_b32_e32 v21, v0
	v_mov_b32_e32 v22, v0
	v_mov_b32_e32 v23, v0
	v_mov_b32_e32 v24, v0
	v_mov_b32_e32 v25, v0
	v_mov_b32_e32 v26, v0
	v_mov_b32_e32 v27, v0
	v_mov_b32_e32 v28, v0
	v_mov_b32_e32 v29, v0
	v_mov_b32_e32 v30, v0
	v_mov_b32_e32 v31, v0
	v_mov_b32_e32 v32, v0
	v_mov_b32_e32 v33, v0
	v_mov_b32_e32 v34, v0
	v_mov_b32_e32 v35, v0
	v_mov_b32_e32 v36, v0
	v_mov_b32_e32 v37, v0
	v_mov_b32_e32 v38, v0
	v_mov_b32_e32 v39, v0
	v_mov_b32_e32 v40, v0
	v_mov_b32_e32 v41, v0
	v_mov_b32_e32 v42, v0
	v_mov_b32_e32 v43, v0
	v_mov_b32_e32 v44, v0
	v_mov_b32_e32 v45, v0
	v_mov_b32_e32 v46, v0
	v_mov_b32_e32 v47, v0
	v_mov_b32_e32 v48, v0
	v_mov_b32_e32 v49, v0
	v_mov_b32_e32 v50, v0
	v_mov_b32_e32 v51, v0
	v_mov_b32_e32 v52, v0
	v_mov_b32_e32 v53, v0
	v_mov_b32_e32 v54, v0
	v_mov_b32_e32 v55, v0
	v_mov_b32_e32 v56, v0
	v_mov_b32_e32 v57, v0
	v_mov_b32_e32 v58, v0
	v_mov_b32_e32 v59, v0
	v_mov_b32_e32 v60, v0
	v_mov_b32_e32 v61, v0
	v_mov_b32_e32 v62, v0
	v_mov_b32_e32 v63, v0
	v_mov_b32_e32 v64, v0
	v_mov_b32_e32 v65, v0
	v_mov_b32_e32 v66, v0
	v_mov_b32_e32 v67, v0
	v_mov_b32_e32 v68, v0
	v_mov_b32_e32 v69, v0
	v_mov_b32_e32 v70, v0
	v_mov_b32_e32 v71, v0
	v_mov_b32_e32 v72, v0
	v_mov_b32_e32 v73, v0
	v_mov_b32_e32 v74, v0
	v_mov_b32_e32 v75, v0
	v_mov_b32_e32 v76, v0
	v_mov_b32_e32 v77, v0
	v_mov_b32_e32 v78, v0
	v_mov_b32_e32 v79, v0
	v_mov_b32_e32 v80, v0
	v_mov_b32_e32 v81, v0
	v_mov_b32_e32 v82, v0
	v_mov_b32_e32 v83, v0
	v_mov_b32_e32 v84, v0
	v_mov_b32_e32 v85, v0
	v_mov_b32_e32 v86, v0
	v_mov_b32_e32 v87, v0
	v_mov_b32_e32 v88, v0
	v_mov_b32_e32 v89, v0
	v_mov_b32_e32 v90, v0
	v_mov_b32_e32 v91, v0
	v_mov_b32_e32 v92, v0
	v_mov_b32_e32 v93, v0
	v_mov_b32_e32 v94, v0
	v_mov_b32_e32 v95, v0
	v_mov_b32_e32 v96, v0
	v_mov_b32_e32 v97, v0
	v_mov_b32_e32 v98, v0
	v_mov_b32_e32 v99, v0
	v_mov_b32_e32 v100, v0
	v_mov_b32_e32 v101, v0
	v_mov_b32_e32 v102, v0
	v_mov_b32_e32 v103, v0
	v_mov_b32_e32 v104, v0
	v_mov_b32_e32 v105, v0
	v_mov_b32_e32 v106, v0
	v_mov_b32_e32 v107, v0
	v_mov_b32_e32 v108, v0
	v_mov_b32_e32 v109, v0
	v_mov_b32_e32 v110, v0
	v_mov_b32_e32 v111, v0
	v_mov_b32_e32 v112, v0
	v_mov_b32_e32 v113, v0
	v_mov_b32_e32 v114, v0
	v_mov_b32_e32 v115, v0
	v_mov_b32_e32 v116, v0
	v_mov_b32_e32 v117, v0
	v_mov_b32_e32 v118, v0
	v_mov_b32_e32 v119, v0
	v_mov_b32_e32 v120, v0
	v_mov_b32_e32 v121, v0
	v_mov_b32_e32 v122, v0
	v_mov_b32_e32 v123, v0
	v_mov_b32_e32 v124, v0
	v_mov_b32_e32 v125, v0
	v_mov_b32_e32 v126, v0
	v_mov_b32_e32 v127, v0
	s_add_i32 s60, s59, 0x10000
	s_and_b32 s22, s60, 0x10000
	s_add_i32 s61, s22, s24
	s_add_i32 s62, s61, 0x8000
	s_add_u32 s22, s56, s20
	s_addc_u32 s23, s57, s21
	s_mov_b32 m0, s61
	global_load_lds_dwordx4 v147, s[22:23]
	s_add_u32 s22, s54, s20
	s_addc_u32 s23, s55, s21
	s_add_i32 s63, s61, 0x400
	s_mov_b32 m0, s63
	global_load_lds_dwordx4 v148, s[22:23]
	s_add_u32 s22, s52, s20
	s_addc_u32 s23, s53, s21
	s_add_i32 s63, s61, 0x800
	s_mov_b32 m0, s63
	global_load_lds_dwordx4 v147, s[22:23]
	s_add_u32 s22, s50, s20
	s_addc_u32 s23, s51, s21
	s_add_i32 s63, s61, 0xc00
	s_mov_b32 m0, s63
	global_load_lds_dwordx4 v148, s[22:23]
	s_add_u32 s22, s48, s20
	s_addc_u32 s23, s49, s21
	s_mov_b32 m0, s62
	global_load_lds_dwordx4 v149, s[22:23]
	s_add_u32 s22, s46, s20
	s_addc_u32 s23, s47, s21
	s_add_i32 s62, s61, 0x8400
	s_mov_b32 m0, s62
	global_load_lds_dwordx4 v150, s[22:23]
	s_add_u32 s22, s44, s20
	s_addc_u32 s23, s45, s21
	s_add_i32 s62, s61, 0x8800
	s_mov_b32 m0, s62
	global_load_lds_dwordx4 v149, s[22:23]
	s_add_u32 s22, s25, s20
	s_addc_u32 s23, s43, s21
	s_add_i32 s61, s61, 0x8c00
	s_mov_b32 m0, s61
	global_load_lds_dwordx4 v150, s[22:23]
	s_branch .LBB0_327

.LBB0_395:
	s_lshl_b32 s4, s30, 3
	s_and_b32 s4, s4, 56
	s_bfe_u32 s5, s30, 0x30003
	s_or_b32 s4, s4, s5
	s_lshl_b32 s5, s30, 2
	s_lshr_b32 s12, s30, 3
	s_and_b32 s8, s5, 0xffffff00
	s_lshl_b32 s4, s4, 19
	s_add_u32 s10, s18, s4
	s_addc_u32 s11, s19, 0
	s_ashr_i32 s9, s8, 31
	s_lshl_b64 s[4:5], s[8:9], 11
	s_add_u32 s9, s20, s4
	v_readfirstlane_b32 s4, v146
	s_addc_u32 s13, s21, s5
	s_ashr_i32 s14, s4, 6
	s_lshl_b32 s4, s14, 5
	s_ashr_i32 s5, s4, 31
	s_lshl_b64 s[4:5], s[4:5], 11
	s_add_u32 s10, s10, s4
	s_addc_u32 s11, s11, s5
	s_add_u32 s4, s9, s4
	s_addc_u32 s5, s13, s5
	s_lshl_b32 s9, s14, 12
	s_add_i32 s13, s9, 0x8000
	s_add_u32 s14, s10, 0x4000
	s_barrier
	s_mov_b32 m0, s9
	global_load_lds_dwordx4 v147, s[10:11]
	s_addc_u32 s15, s11, 0
	s_or_b32 s16, s9, 0x400
	s_mov_b32 m0, s16
	global_load_lds_dwordx4 v148, s[14:15]
	s_add_u32 s14, s10, 0x8000
	s_addc_u32 s15, s11, 0
	s_or_b32 s16, s9, 0x800
	s_mov_b32 m0, s16
	global_load_lds_dwordx4 v147, s[14:15]
	s_add_u32 s14, s10, 0xc000
	s_addc_u32 s15, s11, 0
	s_or_b32 s16, s9, 0xc00
	s_mov_b32 m0, s16
	global_load_lds_dwordx4 v148, s[14:15]
	s_add_u32 s14, s4, 0x4000
	s_mov_b32 m0, s13
	global_load_lds_dwordx4 v147, s[4:5]
	s_addc_u32 s15, s5, 0
	s_add_i32 s13, s9, 0x8400
	s_mov_b32 m0, s13
	global_load_lds_dwordx4 v148, s[14:15]
	s_add_u32 s14, s4, 0x8000
	s_addc_u32 s15, s5, 0
	s_add_i32 s13, s9, 0x8800
	s_mov_b32 m0, s13
	global_load_lds_dwordx4 v147, s[14:15]
	s_add_u32 s14, s4, 0xc000
	s_addc_u32 s15, s5, 0
	s_add_i32 s13, s9, 0x8c00
	s_mov_b32 m0, s13
	global_load_lds_dwordx4 v148, s[14:15]
	s_add_u32 s13, s4, 0xc080
	s_addc_u32 s14, s5, 0
	s_add_u32 s15, s4, 0x8080
	s_addc_u32 s16, s5, 0
	s_add_u32 s17, s4, 0x4080
	s_addc_u32 s31, s5, 0
	s_add_u32 s33, s4, 0x80
	s_addc_u32 s34, s5, 0
	s_add_u32 s35, s10, 0xc080
	s_addc_u32 s36, s11, 0
	s_add_u32 s37, s10, 0x8080
	s_addc_u32 s38, s11, 0
	s_add_u32 s39, s10, 0x4080
	s_addc_u32 s40, s11, 0
	s_add_u32 s41, s10, 0x80
	s_addc_u32 s42, s11, 0
	s_mov_b64 s[4:5], 0
	s_mov_b32 s44, 0
	s_mov_b32 s43, 0
	v_mov_b32_e32 v0, 0
	v_mov_b32_e32 v1, v129
	v_mov_b32_e32 v2, v129
	v_mov_b32_e32 v3, v129
	v_mov_b32_e32 v4, v129
	v_mov_b32_e32 v5, v129
	v_mov_b32_e32 v6, v129
	v_mov_b32_e32 v7, v129
	v_mov_b32_e32 v8, v129
	v_mov_b32_e32 v9, v129
	v_mov_b32_e32 v10, v129
	v_mov_b32_e32 v11, v129
	v_mov_b32_e32 v12, v129
	v_mov_b32_e32 v13, v129
	v_mov_b32_e32 v14, v129
	v_mov_b32_e32 v15, v129
	v_mov_b32_e32 v16, 0
	v_mov_b32_e32 v17, v129
	v_mov_b32_e32 v18, v129
	v_mov_b32_e32 v19, v129
	v_mov_b32_e32 v20, v129
	v_mov_b32_e32 v21, v129
	v_mov_b32_e32 v22, v129
	v_mov_b32_e32 v23, v129
	v_mov_b32_e32 v24, v129
	v_mov_b32_e32 v25, v129
	v_mov_b32_e32 v26, v129
	v_mov_b32_e32 v27, v129
	v_mov_b32_e32 v28, v129
	v_mov_b32_e32 v29, v129
	v_mov_b32_e32 v30, v129
	v_mov_b32_e32 v31, v129
	v_mov_b32_e32 v32, 0
	v_mov_b32_e32 v33, v129
	v_mov_b32_e32 v34, v129
	v_mov_b32_e32 v35, v129
	v_mov_b32_e32 v36, v129
	v_mov_b32_e32 v37, v129
	v_mov_b32_e32 v38, v129
	v_mov_b32_e32 v39, v129
	v_mov_b32_e32 v40, v129
	v_mov_b32_e32 v41, v129
	v_mov_b32_e32 v42, v129
	v_mov_b32_e32 v43, v129
	v_mov_b32_e32 v44, v129
	v_mov_b32_e32 v45, v129
	v_mov_b32_e32 v46, v129
	v_mov_b32_e32 v47, v129
	v_mov_b32_e32 v48, 0
	v_mov_b32_e32 v49, v129
	v_mov_b32_e32 v50, v129
	v_mov_b32_e32 v51, v129
	v_mov_b32_e32 v52, v129
	v_mov_b32_e32 v53, v129
	v_mov_b32_e32 v54, v129
	v_mov_b32_e32 v55, v129
	v_mov_b32_e32 v56, v129
	v_mov_b32_e32 v57, v129
	v_mov_b32_e32 v58, v129
	v_mov_b32_e32 v59, v129
	v_mov_b32_e32 v60, v129
	v_mov_b32_e32 v61, v129
	v_mov_b32_e32 v62, v129
	v_mov_b32_e32 v63, v129
	v_mov_b32_e32 v64, 0
	v_mov_b32_e32 v65, v129
	v_mov_b32_e32 v66, v129
	v_mov_b32_e32 v67, v129
	v_mov_b32_e32 v68, v129
	v_mov_b32_e32 v69, v129
	v_mov_b32_e32 v70, v129
	v_mov_b32_e32 v71, v129
	v_mov_b32_e32 v72, v129
	v_mov_b32_e32 v73, v129
	v_mov_b32_e32 v74, v129
	v_mov_b32_e32 v75, v129
	v_mov_b32_e32 v76, v129
	v_mov_b32_e32 v77, v129
	v_mov_b32_e32 v78, v129
	v_mov_b32_e32 v79, v129
	v_mov_b32_e32 v80, 0
	v_mov_b32_e32 v81, v129
	v_mov_b32_e32 v82, v129
	v_mov_b32_e32 v83, v129
	v_mov_b32_e32 v84, v129
	v_mov_b32_e32 v85, v129
	v_mov_b32_e32 v86, v129
	v_mov_b32_e32 v87, v129
	v_mov_b32_e32 v88, v129
	v_mov_b32_e32 v89, v129
	v_mov_b32_e32 v90, v129
	v_mov_b32_e32 v91, v129
	v_mov_b32_e32 v92, v129
	v_mov_b32_e32 v93, v129
	v_mov_b32_e32 v94, v129
	v_mov_b32_e32 v95, v129
	v_mov_b32_e32 v96, 0
	v_mov_b32_e32 v97, v129
	v_mov_b32_e32 v98, v129
	v_mov_b32_e32 v99, v129
	v_mov_b32_e32 v100, v129
	v_mov_b32_e32 v101, v129
	v_mov_b32_e32 v102, v129
	v_mov_b32_e32 v103, v129
	v_mov_b32_e32 v104, v129
	v_mov_b32_e32 v105, v129
	v_mov_b32_e32 v106, v129
	v_mov_b32_e32 v107, v129
	v_mov_b32_e32 v108, v129
	v_mov_b32_e32 v109, v129
	v_mov_b32_e32 v110, v129
	v_mov_b32_e32 v111, v129
	v_mov_b32_e32 v112, 0
	v_mov_b32_e32 v113, v129
	v_mov_b32_e32 v114, v129
	v_mov_b32_e32 v115, v129
	v_mov_b32_e32 v116, v129
	v_mov_b32_e32 v117, v129
	v_mov_b32_e32 v118, v129
	v_mov_b32_e32 v119, v129
	v_mov_b32_e32 v120, v129
	v_mov_b32_e32 v121, v129
	v_mov_b32_e32 v122, v129
	v_mov_b32_e32 v123, v129
	v_mov_b32_e32 v124, v129
	v_mov_b32_e32 v125, v129
	v_mov_b32_e32 v126, v129
	v_mov_b32_e32 v127, v129
	s_add_i32 s45, s44, 0x10000
	s_and_b32 s10, s45, 0x10000
	s_add_i32 s46, s10, s9
	s_add_i32 s47, s46, 0x8000
	s_add_u32 s10, s41, s4
	s_addc_u32 s11, s42, s5
	s_mov_b32 m0, s46
	global_load_lds_dwordx4 v147, s[10:11]
	s_add_u32 s10, s39, s4
	s_addc_u32 s11, s40, s5
	s_add_i32 s48, s46, 0x400
	s_mov_b32 m0, s48
	global_load_lds_dwordx4 v148, s[10:11]
	s_add_u32 s10, s37, s4
	s_addc_u32 s11, s38, s5
	s_add_i32 s48, s46, 0x800
	s_mov_b32 m0, s48
	global_load_lds_dwordx4 v147, s[10:11]
	s_add_u32 s10, s35, s4
	s_addc_u32 s11, s36, s5
	s_add_i32 s48, s46, 0xc00
	s_mov_b32 m0, s48
	global_load_lds_dwordx4 v148, s[10:11]
	s_add_u32 s10, s33, s4
	s_addc_u32 s11, s34, s5
	s_mov_b32 m0, s47
	global_load_lds_dwordx4 v147, s[10:11]
	s_add_u32 s10, s17, s4
	s_addc_u32 s11, s31, s5
	s_add_i32 s47, s46, 0x8400
	s_mov_b32 m0, s47
	global_load_lds_dwordx4 v148, s[10:11]
	s_add_u32 s10, s15, s4
	s_addc_u32 s11, s16, s5
	s_add_i32 s47, s46, 0x8800
	s_mov_b32 m0, s47
	global_load_lds_dwordx4 v147, s[10:11]
	s_add_u32 s10, s13, s4
	s_addc_u32 s11, s14, s5
	s_add_i32 s46, s46, 0x8c00
	s_mov_b32 m0, s46
	global_load_lds_dwordx4 v148, s[10:11]
	s_branch .LBB0_397

.LBB0_397:
	s_waitcnt vmcnt(0)
	s_barrier
	s_and_b32 s10, s44, 0x10000
	v_or_b32_e32 v128, s10, v150
	v_add_u32_e32 v155, v128, v151
	ds_read_b128 v[130:133], v155 offset:32768
	ds_read_b128 v[160:163], v155 offset:36864
	v_add_u32_e32 v176, s10, v149
	v_add_u32_e32 v156, v176, v151
	ds_read_b128 v[134:137], v156
	ds_read_b128 v[138:141], v156 offset:4096
	ds_read_b128 v[142:145], v156 offset:8192
	v_add_u32_e32 v155, v176, v152
	ds_read_b128 v[156:159], v156 offset:12288
	s_sub_u32 s101, s43, 1
	s_cmp_lt_u32 s101, 14
	s_mov_b64 s[10:11], -1
	s_cbranch_scc1 .LBB0_399
	s_add_i32 s45, s44, 0x10000
	s_mov_b64 s[10:11], 0

.LBB0_468:
	s_lshl_b32 s0, s27, 3
	s_and_b32 s0, s0, 56
	s_bfe_u32 s1, s27, 0x30003
	s_or_b32 s29, s0, s1
	s_ashr_i32 s28, s27, 6
	s_lshl_b32 s0, s28, 8
	s_lshl_b32 s1, s29, 19
	s_add_u32 s18, s13, s1
	s_addc_u32 s19, s15, 0
	s_ashr_i32 s1, s0, 31
	s_lshl_b64 s[0:1], s[0:1], 11
	s_add_u32 s30, s20, s0
	v_readfirstlane_b32 s0, v152
	s_addc_u32 s31, s21, s1
	s_ashr_i32 s33, s0, 6
	s_lshl_b32 s0, s33, 5
	s_ashr_i32 s1, s0, 31
	s_lshl_b64 s[0:1], s[0:1], 11
	s_add_u32 s18, s18, s0
	s_addc_u32 s19, s19, s1
	s_add_u32 s0, s30, s0
	s_addc_u32 s1, s31, s1
	s_lshl_b32 s30, s33, 12
	s_add_i32 s31, s30, 0x8000
	s_add_u32 s34, s18, 0x4000
	s_barrier
	s_mov_b32 m0, s30
	global_load_lds_dwordx4 v153, s[18:19]
	s_addc_u32 s35, s19, 0
	s_or_b32 s33, s30, 0x400
	s_mov_b32 m0, s33
	global_load_lds_dwordx4 v154, s[34:35]
	s_add_u32 s34, s18, 0x8000
	s_addc_u32 s35, s19, 0
	s_or_b32 s33, s30, 0x800
	s_mov_b32 m0, s33
	global_load_lds_dwordx4 v153, s[34:35]
	s_add_u32 s34, s18, 0xc000
	s_addc_u32 s35, s19, 0
	s_or_b32 s33, s30, 0xc00
	s_mov_b32 m0, s33
	global_load_lds_dwordx4 v154, s[34:35]
	s_add_u32 s34, s0, 0x4000
	s_mov_b32 m0, s31
	global_load_lds_dwordx4 v153, s[0:1]
	s_addc_u32 s35, s1, 0
	s_add_i32 s31, s30, 0x8400
	s_mov_b32 m0, s31
	global_load_lds_dwordx4 v154, s[34:35]
	s_add_u32 s34, s0, 0x8000
	s_addc_u32 s35, s1, 0
	s_add_i32 s31, s30, 0x8800
	s_mov_b32 m0, s31
	global_load_lds_dwordx4 v153, s[34:35]
	s_add_u32 s34, s0, 0xc000
	s_addc_u32 s35, s1, 0
	s_add_i32 s31, s30, 0x8c00
	s_mov_b32 m0, s31
	global_load_lds_dwordx4 v154, s[34:35]
	s_add_u32 s31, s0, 0xc080
	s_addc_u32 s33, s1, 0
	s_add_u32 s34, s0, 0x8080
	s_addc_u32 s35, s1, 0
	s_add_u32 s36, s0, 0x4080
	s_addc_u32 s37, s1, 0
	s_add_u32 s38, s0, 0x80
	s_addc_u32 s39, s1, 0
	s_add_u32 s40, s18, 0xc080
	s_addc_u32 s41, s19, 0
	s_add_u32 s42, s18, 0x8080
	s_addc_u32 s43, s19, 0
	s_add_u32 s44, s18, 0x4080
	s_addc_u32 s45, s19, 0
	s_add_u32 s46, s18, 0x80
	s_addc_u32 s47, s19, 0
	s_mov_b64 s[0:1], 0
	s_mov_b32 s49, 0
	s_mov_b32 s48, 0
	s_waitcnt lgkmcnt(14)
	v_mov_b32_e32 v0, 0
	v_mov_b32_e32 v1, v145
	s_waitcnt lgkmcnt(13)
	v_mov_b32_e32 v2, v145
	s_waitcnt lgkmcnt(12)
	v_mov_b32_e32 v3, v145
	s_waitcnt lgkmcnt(11)
	v_mov_b32_e32 v4, v145
	s_waitcnt lgkmcnt(10)
	v_mov_b32_e32 v5, v145
	v_mov_b32_e32 v6, v145
	s_waitcnt lgkmcnt(9)
	v_mov_b32_e32 v7, v145
	s_waitcnt lgkmcnt(8)
	v_mov_b32_e32 v8, v145
	s_waitcnt lgkmcnt(7)
	v_mov_b32_e32 v9, v145
	s_waitcnt lgkmcnt(6)
	v_mov_b32_e32 v10, v145
	s_waitcnt lgkmcnt(5)
	v_mov_b32_e32 v11, v145
	s_waitcnt lgkmcnt(4)
	v_mov_b32_e32 v12, v145
	v_mov_b32_e32 v13, v145
	s_waitcnt lgkmcnt(3)
	v_mov_b32_e32 v14, v145
	s_waitcnt lgkmcnt(2)
	v_mov_b32_e32 v15, v145
	s_waitcnt lgkmcnt(1)
	v_mov_b32_e32 v16, 0
	v_mov_b32_e32 v17, v145
	v_mov_b32_e32 v18, v145
	v_mov_b32_e32 v19, v145
	v_mov_b32_e32 v20, v145
	v_mov_b32_e32 v21, v145
	v_mov_b32_e32 v22, v145
	v_mov_b32_e32 v23, v145
	v_mov_b32_e32 v24, v145
	v_mov_b32_e32 v25, v145
	v_mov_b32_e32 v26, v145
	v_mov_b32_e32 v27, v145
	v_mov_b32_e32 v28, v145
	v_mov_b32_e32 v29, v145
	v_mov_b32_e32 v30, v145
	v_mov_b32_e32 v31, v145
	v_mov_b32_e32 v32, 0
	v_mov_b32_e32 v33, v145
	v_mov_b32_e32 v34, v145
	v_mov_b32_e32 v35, v145
	v_mov_b32_e32 v36, v145
	v_mov_b32_e32 v37, v145
	v_mov_b32_e32 v38, v145
	v_mov_b32_e32 v39, v145
	v_mov_b32_e32 v40, v145
	v_mov_b32_e32 v41, v145
	v_mov_b32_e32 v42, v145
	v_mov_b32_e32 v43, v145
	v_mov_b32_e32 v44, v145
	v_mov_b32_e32 v45, v145
	v_mov_b32_e32 v46, v145
	s_waitcnt lgkmcnt(0)
	v_mov_b32_e32 v47, v145
	v_mov_b32_e32 v48, 0
	v_mov_b32_e32 v49, v145
	v_mov_b32_e32 v50, v145
	v_mov_b32_e32 v51, v145
	v_mov_b32_e32 v52, v145
	v_mov_b32_e32 v53, v145
	v_mov_b32_e32 v54, v145
	v_mov_b32_e32 v55, v145
	v_mov_b32_e32 v56, v145
	v_mov_b32_e32 v57, v145
	v_mov_b32_e32 v58, v145
	v_mov_b32_e32 v59, v145
	v_mov_b32_e32 v60, v145
	v_mov_b32_e32 v61, v145
	v_mov_b32_e32 v62, v145
	v_mov_b32_e32 v63, v145
	v_mov_b32_e32 v64, 0
	v_mov_b32_e32 v65, v145
	v_mov_b32_e32 v66, v145
	v_mov_b32_e32 v67, v145
	v_mov_b32_e32 v68, v145
	v_mov_b32_e32 v69, v145
	v_mov_b32_e32 v70, v145
	v_mov_b32_e32 v71, v145
	v_mov_b32_e32 v72, v145
	v_mov_b32_e32 v73, v145
	v_mov_b32_e32 v74, v145
	v_mov_b32_e32 v75, v145
	v_mov_b32_e32 v76, v145
	v_mov_b32_e32 v77, v145
	v_mov_b32_e32 v78, v145
	v_mov_b32_e32 v79, v145
	v_mov_b32_e32 v80, 0
	v_mov_b32_e32 v81, v145
	v_mov_b32_e32 v82, v145
	v_mov_b32_e32 v83, v145
	v_mov_b32_e32 v84, v145
	v_mov_b32_e32 v85, v145
	v_mov_b32_e32 v86, v145
	v_mov_b32_e32 v87, v145
	v_mov_b32_e32 v88, v145
	v_mov_b32_e32 v89, v145
	v_mov_b32_e32 v90, v145
	v_mov_b32_e32 v91, v145
	v_mov_b32_e32 v92, v145
	v_mov_b32_e32 v93, v145
	v_mov_b32_e32 v94, v145
	v_mov_b32_e32 v95, v145
	v_mov_b32_e32 v96, 0
	v_mov_b32_e32 v97, v145
	v_mov_b32_e32 v98, v145
	v_mov_b32_e32 v99, v145
	v_mov_b32_e32 v100, v145
	v_mov_b32_e32 v101, v145
	v_mov_b32_e32 v102, v145
	v_mov_b32_e32 v103, v145
	v_mov_b32_e32 v104, v145
	v_mov_b32_e32 v105, v145
	v_mov_b32_e32 v106, v145
	v_mov_b32_e32 v107, v145
	v_mov_b32_e32 v108, v145
	v_mov_b32_e32 v109, v145
	v_mov_b32_e32 v110, v145
	v_mov_b32_e32 v111, v145
	v_mov_b32_e32 v112, 0
	v_mov_b32_e32 v113, v145
	v_mov_b32_e32 v114, v145
	v_mov_b32_e32 v115, v145
	v_mov_b32_e32 v116, v145
	v_mov_b32_e32 v117, v145
	v_mov_b32_e32 v118, v145
	v_mov_b32_e32 v119, v145
	v_mov_b32_e32 v120, v145
	v_mov_b32_e32 v121, v145
	v_mov_b32_e32 v122, v145
	v_mov_b32_e32 v123, v145
	v_mov_b32_e32 v124, v145
	v_mov_b32_e32 v125, v145
	v_mov_b32_e32 v126, v145
	v_mov_b32_e32 v127, v145
	s_add_i32 s50, s49, 0x10000
	s_and_b32 s18, s50, 0x10000
	s_add_i32 s51, s18, s30
	s_add_i32 s52, s51, 0x8000
	s_add_u32 s18, s46, s0
	s_addc_u32 s19, s47, s1
	s_mov_b32 m0, s51
	global_load_lds_dwordx4 v153, s[18:19]
	s_add_u32 s18, s44, s0
	s_addc_u32 s19, s45, s1
	s_add_i32 s53, s51, 0x400
	s_mov_b32 m0, s53
	global_load_lds_dwordx4 v154, s[18:19]
	s_add_u32 s18, s42, s0
	s_addc_u32 s19, s43, s1
	s_add_i32 s53, s51, 0x800
	s_mov_b32 m0, s53
	global_load_lds_dwordx4 v153, s[18:19]
	s_add_u32 s18, s40, s0
	s_addc_u32 s19, s41, s1
	s_add_i32 s53, s51, 0xc00
	s_mov_b32 m0, s53
	global_load_lds_dwordx4 v154, s[18:19]
	s_add_u32 s18, s38, s0
	s_addc_u32 s19, s39, s1
	s_mov_b32 m0, s52
	global_load_lds_dwordx4 v153, s[18:19]
	s_add_u32 s18, s36, s0
	s_addc_u32 s19, s37, s1
	s_add_i32 s52, s51, 0x8400
	s_mov_b32 m0, s52
	global_load_lds_dwordx4 v154, s[18:19]
	s_add_u32 s18, s34, s0
	s_addc_u32 s19, s35, s1
	s_add_i32 s52, s51, 0x8800
	s_mov_b32 m0, s52
	global_load_lds_dwordx4 v153, s[18:19]
	s_add_u32 s18, s31, s0
	s_addc_u32 s19, s33, s1
	s_add_i32 s51, s51, 0x8c00
	s_mov_b32 m0, s51
	global_load_lds_dwordx4 v154, s[18:19]
	s_branch .LBB0_470

.LBB0_470:
	s_waitcnt vmcnt(0)
	s_barrier
	s_and_b32 s18, s49, 0x10000
	v_or_b32_e32 v144, s18, v156
	v_add_u32_e32 v150, v144, v157
	ds_read_b128 v[128:131], v150 offset:32768
	ds_read_b128 v[164:167], v150 offset:36864
	v_add_u32_e32 v151, s18, v155
	v_add_u32_e32 v146, v151, v157
	ds_read_b128 v[132:135], v146
	ds_read_b128 v[136:139], v146 offset:4096
	ds_read_b128 v[140:143], v146 offset:8192
	v_add_u32_e32 v150, v151, v158
	ds_read_b128 v[146:149], v146 offset:12288
	s_sub_u32 s101, s48, 1
	s_cmp_lt_u32 s101, 14
	s_mov_b64 s[18:19], -1
	s_cbranch_scc1 .LBB0_472
	s_add_i32 s50, s49, 0x10000
	s_mov_b64 s[18:19], 0

.LBB0_896:
	s_lshl_b32 s16, s39, 3
	s_and_b32 s16, s16, 56
	s_bfe_u32 s17, s39, 0x30003
	s_or_b32 s17, s16, s17
	s_lshl_b32 s16, s39, 2
	s_lshr_b32 s22, s39, 3
	s_and_b32 s16, s16, 0xffffff00
	s_lshl_b32 s42, s17, 18
	s_lshl_b32 s17, s17, 19
	s_add_u32 s23, s24, s17
	s_addc_u32 s33, s25, 0
	s_ashr_i32 s17, s16, 31
	s_lshl_b64 s[18:19], s[16:17], 9
	s_lshl_b64 s[16:17], s[16:17], 10
	s_add_u32 s40, s26, s16
	v_readfirstlane_b32 s16, v146
	s_addc_u32 s41, s27, s17
	s_ashr_i32 s43, s16, 6
	s_lshl_b32 s16, s43, 5
	s_ashr_i32 s17, s16, 31
	s_lshl_b64 s[20:21], s[16:17], 11
	s_add_u32 s20, s23, s20
	s_addc_u32 s21, s33, s21
	s_lshl_b64 s[16:17], s[16:17], 10
	s_add_u32 s16, s40, s16
	s_addc_u32 s17, s41, s17
	s_lshl_b32 s23, s43, 12
	s_add_i32 s33, s23, 0x8000
	s_add_u32 s40, s20, 0x4000
	s_barrier
	s_mov_b32 m0, s23
	global_load_lds_dwordx4 v147, s[20:21]
	s_addc_u32 s41, s21, 0
	s_or_b32 s43, s23, 0x400
	s_mov_b32 m0, s43
	global_load_lds_dwordx4 v148, s[40:41]
	s_add_u32 s40, s20, 0x8000
	s_addc_u32 s41, s21, 0
	s_or_b32 s43, s23, 0x800
	s_mov_b32 m0, s43
	global_load_lds_dwordx4 v147, s[40:41]
	s_add_u32 s40, s20, 0xc000
	s_addc_u32 s41, s21, 0
	s_or_b32 s43, s23, 0xc00
	s_mov_b32 m0, s43
	global_load_lds_dwordx4 v148, s[40:41]
	s_add_u32 s40, s16, 0x2000
	s_mov_b32 m0, s33
	global_load_lds_dwordx4 v149, s[16:17]
	s_addc_u32 s41, s17, 0
	s_add_i32 s33, s23, 0x8400
	s_mov_b32 m0, s33
	global_load_lds_dwordx4 v150, s[40:41]
	s_add_u32 s40, s16, 0x4000
	s_addc_u32 s41, s17, 0
	s_add_i32 s33, s23, 0x8800
	s_mov_b32 m0, s33
	global_load_lds_dwordx4 v149, s[40:41]
	s_add_u32 s40, s16, 0x6000
	s_addc_u32 s41, s17, 0
	s_add_i32 s33, s23, 0x8c00
	s_mov_b32 m0, s33
	global_load_lds_dwordx4 v150, s[40:41]
	s_add_u32 s33, s16, 0x6080
	s_addc_u32 s40, s17, 0
	s_add_u32 s41, s16, 0x4080
	s_addc_u32 s43, s17, 0
	s_add_u32 s44, s16, 0x2080
	s_addc_u32 s45, s17, 0
	s_add_u32 s46, s16, 0x80
	s_addc_u32 s47, s17, 0
	s_add_u32 s48, s20, 0xc080
	s_addc_u32 s49, s21, 0
	s_add_u32 s50, s20, 0x8080
	s_addc_u32 s51, s21, 0
	s_add_u32 s52, s20, 0x4080
	s_addc_u32 s53, s21, 0
	s_add_u32 s54, s20, 0x80
	s_addc_u32 s55, s21, 0
	s_mov_b64 s[16:17], 0
	s_mov_b32 s57, 0
	s_mov_b32 s56, 0
	v_mov_b32_e32 v0, 0
	v_mov_b32_e32 v1, v129
	v_mov_b32_e32 v2, v129
	v_mov_b32_e32 v3, v129
	v_mov_b32_e32 v4, v129
	v_mov_b32_e32 v5, v129
	v_mov_b32_e32 v6, v129
	v_mov_b32_e32 v7, v129
	v_mov_b32_e32 v8, v129
	v_mov_b32_e32 v9, v129
	v_mov_b32_e32 v10, v129
	v_mov_b32_e32 v11, v129
	v_mov_b32_e32 v12, v129
	v_mov_b32_e32 v13, v129
	v_mov_b32_e32 v14, v129
	v_mov_b32_e32 v15, v129
	v_mov_b32_e32 v16, 0
	v_mov_b32_e32 v17, v129
	v_mov_b32_e32 v18, v129
	v_mov_b32_e32 v19, v129
	v_mov_b32_e32 v20, v129
	v_mov_b32_e32 v21, v129
	v_mov_b32_e32 v22, v129
	v_mov_b32_e32 v23, v129
	v_mov_b32_e32 v24, v129
	v_mov_b32_e32 v25, v129
	v_mov_b32_e32 v26, v129
	v_mov_b32_e32 v27, v129
	v_mov_b32_e32 v28, v129
	v_mov_b32_e32 v29, v129
	v_mov_b32_e32 v30, v129
	v_mov_b32_e32 v31, v129
	v_mov_b32_e32 v32, 0
	v_mov_b32_e32 v33, v129
	v_mov_b32_e32 v34, v129
	v_mov_b32_e32 v35, v129
	v_mov_b32_e32 v36, v129
	v_mov_b32_e32 v37, v129
	v_mov_b32_e32 v38, v129
	v_mov_b32_e32 v39, v129
	v_mov_b32_e32 v40, v129
	v_mov_b32_e32 v41, v129
	v_mov_b32_e32 v42, v129
	v_mov_b32_e32 v43, v129
	v_mov_b32_e32 v44, v129
	v_mov_b32_e32 v45, v129
	v_mov_b32_e32 v46, v129
	v_mov_b32_e32 v47, v129
	v_mov_b32_e32 v48, 0
	v_mov_b32_e32 v49, v129
	v_mov_b32_e32 v50, v129
	v_mov_b32_e32 v51, v129
	v_mov_b32_e32 v52, v129
	v_mov_b32_e32 v53, v129
	v_mov_b32_e32 v54, v129
	v_mov_b32_e32 v55, v129
	v_mov_b32_e32 v56, v129
	v_mov_b32_e32 v57, v129
	v_mov_b32_e32 v58, v129
	v_mov_b32_e32 v59, v129
	v_mov_b32_e32 v60, v129
	v_mov_b32_e32 v61, v129
	v_mov_b32_e32 v62, v129
	v_mov_b32_e32 v63, v129
	v_mov_b32_e32 v64, 0
	v_mov_b32_e32 v65, v129
	v_mov_b32_e32 v66, v129
	v_mov_b32_e32 v67, v129
	v_mov_b32_e32 v68, v129
	v_mov_b32_e32 v69, v129
	v_mov_b32_e32 v70, v129
	v_mov_b32_e32 v71, v129
	v_mov_b32_e32 v72, v129
	v_mov_b32_e32 v73, v129
	v_mov_b32_e32 v74, v129
	v_mov_b32_e32 v75, v129
	v_mov_b32_e32 v76, v129
	v_mov_b32_e32 v77, v129
	v_mov_b32_e32 v78, v129
	v_mov_b32_e32 v79, v129
	v_mov_b32_e32 v80, 0
	v_mov_b32_e32 v81, v129
	v_mov_b32_e32 v82, v129
	v_mov_b32_e32 v83, v129
	v_mov_b32_e32 v84, v129
	v_mov_b32_e32 v85, v129
	v_mov_b32_e32 v86, v129
	v_mov_b32_e32 v87, v129
	v_mov_b32_e32 v88, v129
	v_mov_b32_e32 v89, v129
	v_mov_b32_e32 v90, v129
	v_mov_b32_e32 v91, v129
	v_mov_b32_e32 v92, v129
	v_mov_b32_e32 v93, v129
	v_mov_b32_e32 v94, v129
	v_mov_b32_e32 v95, v129
	v_mov_b32_e32 v96, 0
	v_mov_b32_e32 v97, v129
	v_mov_b32_e32 v98, v129
	v_mov_b32_e32 v99, v129
	v_mov_b32_e32 v100, v129
	v_mov_b32_e32 v101, v129
	v_mov_b32_e32 v102, v129
	v_mov_b32_e32 v103, v129
	v_mov_b32_e32 v104, v129
	v_mov_b32_e32 v105, v129
	v_mov_b32_e32 v106, v129
	v_mov_b32_e32 v107, v129
	v_mov_b32_e32 v108, v129
	v_mov_b32_e32 v109, v129
	v_mov_b32_e32 v110, v129
	v_mov_b32_e32 v111, v129
	v_mov_b32_e32 v112, 0
	v_mov_b32_e32 v113, v129
	v_mov_b32_e32 v114, v129
	v_mov_b32_e32 v115, v129
	v_mov_b32_e32 v116, v129
	v_mov_b32_e32 v117, v129
	v_mov_b32_e32 v118, v129
	v_mov_b32_e32 v119, v129
	v_mov_b32_e32 v120, v129
	v_mov_b32_e32 v121, v129
	v_mov_b32_e32 v122, v129
	v_mov_b32_e32 v123, v129
	v_mov_b32_e32 v124, v129
	v_mov_b32_e32 v125, v129
	v_mov_b32_e32 v126, v129
	v_mov_b32_e32 v127, v129
	s_add_i32 s58, s57, 0x10000
	s_and_b32 s20, s58, 0x10000
	s_add_i32 s59, s20, s23
	s_add_i32 s60, s59, 0x8000
	s_add_u32 s20, s54, s16
	s_addc_u32 s21, s55, s17
	s_mov_b32 m0, s59
	global_load_lds_dwordx4 v147, s[20:21]
	s_add_u32 s20, s52, s16
	s_addc_u32 s21, s53, s17
	s_add_i32 s61, s59, 0x400
	s_mov_b32 m0, s61
	global_load_lds_dwordx4 v148, s[20:21]
	s_add_u32 s20, s50, s16
	s_addc_u32 s21, s51, s17
	s_add_i32 s61, s59, 0x800
	s_mov_b32 m0, s61
	global_load_lds_dwordx4 v147, s[20:21]
	s_add_u32 s20, s48, s16
	s_addc_u32 s21, s49, s17
	s_add_i32 s61, s59, 0xc00
	s_mov_b32 m0, s61
	global_load_lds_dwordx4 v148, s[20:21]
	s_add_u32 s20, s46, s16
	s_addc_u32 s21, s47, s17
	s_mov_b32 m0, s60
	global_load_lds_dwordx4 v149, s[20:21]
	s_add_u32 s20, s44, s16
	s_addc_u32 s21, s45, s17
	s_add_i32 s60, s59, 0x8400
	s_mov_b32 m0, s60
	global_load_lds_dwordx4 v150, s[20:21]
	s_add_u32 s20, s41, s16
	s_addc_u32 s21, s43, s17
	s_add_i32 s60, s59, 0x8800
	s_mov_b32 m0, s60
	global_load_lds_dwordx4 v149, s[20:21]
	s_add_u32 s20, s33, s16
	s_addc_u32 s21, s40, s17
	s_add_i32 s59, s59, 0x8c00
	s_mov_b32 m0, s59
	global_load_lds_dwordx4 v150, s[20:21]
	s_branch .LBB0_898

.LBB0_898:
	s_waitcnt vmcnt(0)
	s_barrier
	s_and_b32 s20, s57, 0x10000
	v_or_b32_e32 v128, s20, v152
	v_add_u32_e32 v157, v128, v153
	ds_read_b128 v[130:133], v157 offset:32768
	ds_read_b128 v[162:165], v157 offset:36864
	v_add_u32_e32 v180, s20, v151
	v_add_u32_e32 v158, v180, v153
	ds_read_b128 v[134:137], v158
	ds_read_b128 v[138:141], v158 offset:4096
	ds_read_b128 v[142:145], v158 offset:8192
	v_add_u32_e32 v157, v180, v154
	ds_read_b128 v[158:161], v158 offset:12288
	s_sub_u32 s101, s56, 1
	s_cmp_lt_u32 s101, 6
	s_mov_b64 s[20:21], -1
	s_cbranch_scc1 .LBB0_900
	s_add_i32 s58, s57, 0x10000
	s_mov_b64 s[20:21], 0

.LBB0_908:
	v_add_u32_e32 v176, s22, v174
	ds_read_b128 v[182:185], v176
	ds_read_b128 v[186:189], v176 offset:16
	s_add_i32 s22, s22, 0x8200
	s_cmp_lg_u32 s22, 0x20a00
	s_waitcnt vmcnt(3)
	v_lshlrev_b32_e32 v176, 16, v198
	v_and_b32_e32 v177, 0xffff0000, v198
	v_lshlrev_b32_e32 v142, 16, v199
	v_and_b32_e32 v143, 0xffff0000, v199
	v_lshlrev_b32_e32 v180, 16, v200
	v_and_b32_e32 v181, 0xffff0000, v200
	v_lshlrev_b32_e32 v144, 16, v201
	v_and_b32_e32 v145, 0xffff0000, v201
	s_waitcnt lgkmcnt(1)
	v_pk_mul_f32 v[176:177], v[182:183], v[176:177]
	v_pk_mul_f32 v[182:183], v[184:185], v[142:143]
	s_waitcnt lgkmcnt(0)
	v_pk_mul_f32 v[180:181], v[186:187], v[180:181]
	v_pk_mul_f32 v[184:185], v[188:189], v[144:145]
	v_cvt_pk_bf16_f32 v142, v176, v177
	v_cvt_pk_bf16_f32 v143, v182, v183
	v_cvt_pk_bf16_f32 v144, v180, v181
	v_cvt_pk_bf16_f32 v145, v184, v185
	global_store_dwordx4 v[140:141], v[142:145], off offset:-8
	v_lshl_add_u64 v[140:141], v[140:141], 0, s[14:15]
	v_add_u32_e32 v176, s22, v174
	ds_read_b128 v[182:185], v176
	ds_read_b128 v[186:189], v176 offset:16
	s_add_i32 s22, s22, 0x8200
	s_cmp_lg_u32 s22, 0x20a00
	s_waitcnt vmcnt(3)
	v_lshlrev_b32_e32 v176, 16, v202
	v_and_b32_e32 v177, 0xffff0000, v202
	v_lshlrev_b32_e32 v142, 16, v203
	v_and_b32_e32 v143, 0xffff0000, v203
	v_lshlrev_b32_e32 v180, 16, v204
	v_and_b32_e32 v181, 0xffff0000, v204
	v_lshlrev_b32_e32 v144, 16, v205
	v_and_b32_e32 v145, 0xffff0000, v205
	s_waitcnt lgkmcnt(1)
	v_pk_mul_f32 v[176:177], v[182:183], v[176:177]
	v_pk_mul_f32 v[182:183], v[184:185], v[142:143]
	s_waitcnt lgkmcnt(0)
	v_pk_mul_f32 v[180:181], v[186:187], v[180:181]
	v_pk_mul_f32 v[184:185], v[188:189], v[144:145]
	v_cvt_pk_bf16_f32 v142, v176, v177
	v_cvt_pk_bf16_f32 v143, v182, v183
	v_cvt_pk_bf16_f32 v144, v180, v181
	v_cvt_pk_bf16_f32 v145, v184, v185
	global_store_dwordx4 v[140:141], v[142:145], off offset:-8
	v_lshl_add_u64 v[140:141], v[140:141], 0, s[14:15]
	v_add_u32_e32 v176, s22, v174
	ds_read_b128 v[182:185], v176
	ds_read_b128 v[186:189], v176 offset:16
	s_add_i32 s22, s22, 0x8200
	s_cmp_lg_u32 s22, 0x20a00
	s_waitcnt vmcnt(3)
	v_lshlrev_b32_e32 v176, 16, v206
	v_and_b32_e32 v177, 0xffff0000, v206
	v_lshlrev_b32_e32 v142, 16, v207
	v_and_b32_e32 v143, 0xffff0000, v207
	v_lshlrev_b32_e32 v180, 16, v208
	v_and_b32_e32 v181, 0xffff0000, v208
	v_lshlrev_b32_e32 v144, 16, v209
	v_and_b32_e32 v145, 0xffff0000, v209
	s_waitcnt lgkmcnt(1)
	v_pk_mul_f32 v[176:177], v[182:183], v[176:177]
	v_pk_mul_f32 v[182:183], v[184:185], v[142:143]
	s_waitcnt lgkmcnt(0)
	v_pk_mul_f32 v[180:181], v[186:187], v[180:181]
	v_pk_mul_f32 v[184:185], v[188:189], v[144:145]
	v_cvt_pk_bf16_f32 v142, v176, v177
	v_cvt_pk_bf16_f32 v143, v182, v183
	v_cvt_pk_bf16_f32 v144, v180, v181
	v_cvt_pk_bf16_f32 v145, v184, v185
	global_store_dwordx4 v[140:141], v[142:145], off offset:-8
	v_lshl_add_u64 v[140:141], v[140:141], 0, s[14:15]
	v_add_u32_e32 v176, s22, v174
	ds_read_b128 v[182:185], v176
	ds_read_b128 v[186:189], v176 offset:16
	s_add_i32 s22, s22, 0x8200
	s_cmp_lg_u32 s22, 0x20a00
	s_waitcnt vmcnt(3)
	v_lshlrev_b32_e32 v176, 16, v210
	v_and_b32_e32 v177, 0xffff0000, v210
	v_lshlrev_b32_e32 v142, 16, v211
	v_and_b32_e32 v143, 0xffff0000, v211
	v_lshlrev_b32_e32 v180, 16, v212
	v_and_b32_e32 v181, 0xffff0000, v212
	v_lshlrev_b32_e32 v144, 16, v213
	v_and_b32_e32 v145, 0xffff0000, v213
	s_waitcnt lgkmcnt(1)
	v_pk_mul_f32 v[176:177], v[182:183], v[176:177]
	v_pk_mul_f32 v[182:183], v[184:185], v[142:143]
	s_waitcnt lgkmcnt(0)
	v_pk_mul_f32 v[180:181], v[186:187], v[180:181]
	v_pk_mul_f32 v[184:185], v[188:189], v[144:145]
	v_cvt_pk_bf16_f32 v142, v176, v177
	v_cvt_pk_bf16_f32 v143, v182, v183
	v_cvt_pk_bf16_f32 v144, v180, v181
	v_cvt_pk_bf16_f32 v145, v184, v185
	global_store_dwordx4 v[140:141], v[142:145], off offset:-8
	v_lshl_add_u64 v[140:141], v[140:141], 0, s[14:15]
	s_mov_b32 s33, 1
	s_andn2_b64 vcc, exec, s[20:21]
	s_mov_b64 s[20:21], 0
	s_cbranch_vccnz .LBB0_903
	s_lshl_b32 s20, s42, 1
	s_add_u32 s22, s30, s20
	s_addc_u32 s23, s31, 0
	s_lshl_b64 s[18:19], s[18:19], 1
	s_add_u32 s33, s28, s18
	v_readfirstlane_b32 s18, v146
	s_addc_u32 s42, s29, s19
	s_ashr_i32 s43, s18, 6
	s_lshl_b32 s18, s43, 5
	s_ashr_i32 s19, s18, 31
	s_lshl_b64 s[20:21], s[18:19], 11
	s_add_u32 s20, s22, s20
	s_addc_u32 s21, s23, s21
	s_lshl_b64 s[18:19], s[18:19], 10
	s_add_u32 s18, s33, s18
	s_addc_u32 s19, s42, s19
	s_lshl_b32 s22, s43, 12
	s_add_i32 s23, s22, 0x8000
	s_add_u32 s42, s20, 0x4000
	s_barrier
	s_mov_b32 m0, s22
	global_load_lds_dwordx4 v147, s[20:21]
	s_addc_u32 s43, s21, 0
	s_or_b32 s33, s22, 0x400
	s_mov_b32 m0, s33
	global_load_lds_dwordx4 v148, s[42:43]
	s_add_u32 s42, s20, 0x8000
	s_addc_u32 s43, s21, 0
	s_or_b32 s33, s22, 0x800
	s_mov_b32 m0, s33
	global_load_lds_dwordx4 v147, s[42:43]
	s_add_u32 s42, s20, 0xc000
	s_addc_u32 s43, s21, 0
	s_or_b32 s33, s22, 0xc00
	s_mov_b32 m0, s33
	global_load_lds_dwordx4 v148, s[42:43]
	s_add_u32 s42, s18, 0x2000
	s_mov_b32 m0, s23
	global_load_lds_dwordx4 v149, s[18:19]
	s_addc_u32 s43, s19, 0
	s_add_i32 s23, s22, 0x8400
	s_mov_b32 m0, s23
	global_load_lds_dwordx4 v150, s[42:43]
	s_add_u32 s42, s18, 0x4000
	s_addc_u32 s43, s19, 0
	s_add_i32 s23, s22, 0x8800
	s_mov_b32 m0, s23
	global_load_lds_dwordx4 v149, s[42:43]
	s_add_u32 s42, s18, 0x6000
	s_addc_u32 s43, s19, 0
	s_add_i32 s23, s22, 0x8c00
	s_mov_b32 m0, s23
	global_load_lds_dwordx4 v150, s[42:43]
	s_add_u32 s23, s18, 0x6080
	s_addc_u32 s33, s19, 0
	s_add_u32 s42, s18, 0x4080
	s_addc_u32 s43, s19, 0
	s_add_u32 s44, s18, 0x2080
	s_addc_u32 s45, s19, 0
	s_add_u32 s46, s18, 0x80
	s_addc_u32 s47, s19, 0
	s_add_u32 s48, s20, 0xc080
	s_addc_u32 s49, s21, 0
	s_add_u32 s50, s20, 0x8080
	s_addc_u32 s51, s21, 0
	s_add_u32 s52, s20, 0x4080
	s_addc_u32 s53, s21, 0
	s_add_u32 s54, s20, 0x80
	v_mov_b32_e32 v0, 0
	s_addc_u32 s55, s21, 0
	s_mov_b32 s57, 0
	s_mov_b64 s[18:19], 0
	s_mov_b32 s56, 0
	v_mov_b32_e32 v1, v0
	v_mov_b32_e32 v2, v0
	v_mov_b32_e32 v3, v0
	v_mov_b32_e32 v4, v0
	v_mov_b32_e32 v5, v0
	v_mov_b32_e32 v6, v0
	v_mov_b32_e32 v7, v0
	v_mov_b32_e32 v8, v0
	v_mov_b32_e32 v9, v0
	v_mov_b32_e32 v10, v0
	v_mov_b32_e32 v11, v0
	v_mov_b32_e32 v12, v0
	v_mov_b32_e32 v13, v0
	v_mov_b32_e32 v14, v0
	v_mov_b32_e32 v15, v0
	v_mov_b32_e32 v16, v0
	v_mov_b32_e32 v17, v0
	v_mov_b32_e32 v18, v0
	v_mov_b32_e32 v19, v0
	v_mov_b32_e32 v20, v0
	v_mov_b32_e32 v21, v0
	v_mov_b32_e32 v22, v0
	v_mov_b32_e32 v23, v0
	v_mov_b32_e32 v24, v0
	v_mov_b32_e32 v25, v0
	v_mov_b32_e32 v26, v0
	v_mov_b32_e32 v27, v0
	v_mov_b32_e32 v28, v0
	v_mov_b32_e32 v29, v0
	v_mov_b32_e32 v30, v0
	v_mov_b32_e32 v31, v0
	v_mov_b32_e32 v32, v0
	v_mov_b32_e32 v33, v0
	v_mov_b32_e32 v34, v0
	v_mov_b32_e32 v35, v0
	v_mov_b32_e32 v36, v0
	v_mov_b32_e32 v37, v0
	v_mov_b32_e32 v38, v0
	v_mov_b32_e32 v39, v0
	v_mov_b32_e32 v40, v0
	v_mov_b32_e32 v41, v0
	v_mov_b32_e32 v42, v0
	v_mov_b32_e32 v43, v0
	v_mov_b32_e32 v44, v0
	v_mov_b32_e32 v45, v0
	v_mov_b32_e32 v46, v0
	v_mov_b32_e32 v47, v0
	v_mov_b32_e32 v48, v0
	v_mov_b32_e32 v49, v0
	v_mov_b32_e32 v50, v0
	v_mov_b32_e32 v51, v0
	v_mov_b32_e32 v52, v0
	v_mov_b32_e32 v53, v0
	v_mov_b32_e32 v54, v0
	v_mov_b32_e32 v55, v0
	v_mov_b32_e32 v56, v0
	v_mov_b32_e32 v57, v0
	v_mov_b32_e32 v58, v0
	v_mov_b32_e32 v59, v0
	v_mov_b32_e32 v60, v0
	v_mov_b32_e32 v61, v0
	v_mov_b32_e32 v62, v0
	v_mov_b32_e32 v63, v0
	v_mov_b32_e32 v64, v0
	v_mov_b32_e32 v65, v0
	v_mov_b32_e32 v66, v0
	v_mov_b32_e32 v67, v0
	v_mov_b32_e32 v68, v0
	v_mov_b32_e32 v69, v0
	v_mov_b32_e32 v70, v0
	v_mov_b32_e32 v71, v0
	v_mov_b32_e32 v72, v0
	v_mov_b32_e32 v73, v0
	v_mov_b32_e32 v74, v0
	v_mov_b32_e32 v75, v0
	v_mov_b32_e32 v76, v0
	v_mov_b32_e32 v77, v0
	v_mov_b32_e32 v78, v0
	v_mov_b32_e32 v79, v0
	v_mov_b32_e32 v80, v0
	v_mov_b32_e32 v81, v0
	v_mov_b32_e32 v82, v0
	v_mov_b32_e32 v83, v0
	v_mov_b32_e32 v84, v0
	v_mov_b32_e32 v85, v0
	v_mov_b32_e32 v86, v0
	v_mov_b32_e32 v87, v0
	v_mov_b32_e32 v88, v0
	v_mov_b32_e32 v89, v0
	v_mov_b32_e32 v90, v0
	v_mov_b32_e32 v91, v0
	v_mov_b32_e32 v92, v0
	v_mov_b32_e32 v93, v0
	v_mov_b32_e32 v94, v0
	v_mov_b32_e32 v95, v0
	v_mov_b32_e32 v96, v0
	v_mov_b32_e32 v97, v0
	v_mov_b32_e32 v98, v0
	v_mov_b32_e32 v99, v0
	v_mov_b32_e32 v100, v0
	v_mov_b32_e32 v101, v0
	v_mov_b32_e32 v102, v0
	v_mov_b32_e32 v103, v0
	v_mov_b32_e32 v104, v0
	v_mov_b32_e32 v105, v0
	v_mov_b32_e32 v106, v0
	v_mov_b32_e32 v107, v0
	v_mov_b32_e32 v108, v0
	v_mov_b32_e32 v109, v0
	v_mov_b32_e32 v110, v0
	v_mov_b32_e32 v111, v0
	v_mov_b32_e32 v112, v0
	v_mov_b32_e32 v113, v0
	v_mov_b32_e32 v114, v0
	v_mov_b32_e32 v115, v0
	v_mov_b32_e32 v116, v0
	v_mov_b32_e32 v117, v0
	v_mov_b32_e32 v118, v0
	v_mov_b32_e32 v119, v0
	v_mov_b32_e32 v120, v0
	v_mov_b32_e32 v121, v0
	v_mov_b32_e32 v122, v0
	v_mov_b32_e32 v123, v0
	v_mov_b32_e32 v124, v0
	v_mov_b32_e32 v125, v0
	v_mov_b32_e32 v126, v0
	v_mov_b32_e32 v127, v0
	s_add_i32 s58, s57, 0x10000
	s_and_b32 s20, s58, 0x10000
	s_add_i32 s59, s20, s22
	s_add_i32 s60, s59, 0x8000
	s_add_u32 s20, s54, s18
	s_addc_u32 s21, s55, s19
	s_mov_b32 m0, s59
	global_load_lds_dwordx4 v147, s[20:21]
	s_add_u32 s20, s52, s18
	s_addc_u32 s21, s53, s19
	s_add_i32 s61, s59, 0x400
	s_mov_b32 m0, s61
	global_load_lds_dwordx4 v148, s[20:21]
	s_add_u32 s20, s50, s18
	s_addc_u32 s21, s51, s19
	s_add_i32 s61, s59, 0x800
	s_mov_b32 m0, s61
	global_load_lds_dwordx4 v147, s[20:21]
	s_add_u32 s20, s48, s18
	s_addc_u32 s21, s49, s19
	s_add_i32 s61, s59, 0xc00
	s_mov_b32 m0, s61
	global_load_lds_dwordx4 v148, s[20:21]
	s_add_u32 s20, s46, s18
	s_addc_u32 s21, s47, s19
	s_mov_b32 m0, s60
	global_load_lds_dwordx4 v149, s[20:21]
	s_add_u32 s20, s44, s18
	s_addc_u32 s21, s45, s19
	s_add_i32 s60, s59, 0x8400
	s_mov_b32 m0, s60
	global_load_lds_dwordx4 v150, s[20:21]
	s_add_u32 s20, s42, s18
	s_addc_u32 s21, s43, s19
	s_add_i32 s60, s59, 0x8800
	s_mov_b32 m0, s60
	global_load_lds_dwordx4 v149, s[20:21]
	s_add_u32 s20, s23, s18
	s_addc_u32 s21, s33, s19
	s_add_i32 s59, s59, 0x8c00
	s_mov_b32 m0, s59
	global_load_lds_dwordx4 v150, s[20:21]
	s_branch .LBB0_912

.LBB0_980:
	s_lshl_b32 s0, s30, 3
	s_and_b32 s0, s0, 56
	s_bfe_u32 s1, s30, 0x30003
	s_or_b32 s0, s0, s1
	s_lshl_b32 s1, s30, 2
	s_lshr_b32 s12, s30, 3
	s_and_b32 s8, s1, 0xffffff00
	s_lshl_b32 s0, s0, 19
	s_add_u32 s10, s18, s0
	s_addc_u32 s11, s19, 0
	s_ashr_i32 s9, s8, 31
	s_lshl_b64 s[0:1], s[8:9], 11
	s_add_u32 s9, s20, s0
	v_readfirstlane_b32 s0, v144
	s_addc_u32 s13, s21, s1
	s_ashr_i32 s14, s0, 6
	s_lshl_b32 s0, s14, 5
	s_ashr_i32 s1, s0, 31
	s_lshl_b64 s[0:1], s[0:1], 11
	s_add_u32 s10, s10, s0
	s_addc_u32 s11, s11, s1
	s_add_u32 s0, s9, s0
	s_addc_u32 s1, s13, s1
	s_lshl_b32 s9, s14, 12
	s_add_i32 s13, s9, 0x8000
	s_add_u32 s14, s10, 0x4000
	s_barrier
	s_mov_b32 m0, s9
	global_load_lds_dwordx4 v145, s[10:11]
	s_addc_u32 s15, s11, 0
	s_or_b32 s16, s9, 0x400
	s_mov_b32 m0, s16
	global_load_lds_dwordx4 v146, s[14:15]
	s_add_u32 s14, s10, 0x8000
	s_addc_u32 s15, s11, 0
	s_or_b32 s16, s9, 0x800
	s_mov_b32 m0, s16
	global_load_lds_dwordx4 v145, s[14:15]
	s_add_u32 s14, s10, 0xc000
	s_addc_u32 s15, s11, 0
	s_or_b32 s16, s9, 0xc00
	s_mov_b32 m0, s16
	global_load_lds_dwordx4 v146, s[14:15]
	s_add_u32 s14, s0, 0x4000
	s_mov_b32 m0, s13
	global_load_lds_dwordx4 v145, s[0:1]
	s_addc_u32 s15, s1, 0
	s_add_i32 s13, s9, 0x8400
	s_mov_b32 m0, s13
	global_load_lds_dwordx4 v146, s[14:15]
	s_add_u32 s14, s0, 0x8000
	s_addc_u32 s15, s1, 0
	s_add_i32 s13, s9, 0x8800
	s_mov_b32 m0, s13
	global_load_lds_dwordx4 v145, s[14:15]
	s_add_u32 s14, s0, 0xc000
	s_addc_u32 s15, s1, 0
	s_add_i32 s13, s9, 0x8c00
	s_mov_b32 m0, s13
	global_load_lds_dwordx4 v146, s[14:15]
	s_add_u32 s13, s0, 0xc080
	s_addc_u32 s14, s1, 0
	s_add_u32 s15, s0, 0x8080
	s_addc_u32 s16, s1, 0
	s_add_u32 s17, s0, 0x4080
	s_addc_u32 s31, s1, 0
	s_add_u32 s33, s0, 0x80
	s_addc_u32 s34, s1, 0
	s_add_u32 s35, s10, 0xc080
	s_addc_u32 s36, s11, 0
	s_add_u32 s37, s10, 0x8080
	s_addc_u32 s38, s11, 0
	s_add_u32 s39, s10, 0x4080
	s_addc_u32 s40, s11, 0
	s_add_u32 s41, s10, 0x80
	s_addc_u32 s42, s11, 0
	s_mov_b64 s[0:1], 0
	s_mov_b32 s44, 0
	s_mov_b32 s43, 0
	v_mov_b32_e32 v0, 0
	v_mov_b32_e32 v1, v129
	v_mov_b32_e32 v2, v129
	v_mov_b32_e32 v3, v129
	v_mov_b32_e32 v4, v129
	v_mov_b32_e32 v5, v129
	v_mov_b32_e32 v6, v129
	v_mov_b32_e32 v7, v129
	v_mov_b32_e32 v8, v129
	v_mov_b32_e32 v9, v129
	v_mov_b32_e32 v10, v129
	v_mov_b32_e32 v11, v129
	v_mov_b32_e32 v12, v129
	v_mov_b32_e32 v13, v129
	v_mov_b32_e32 v14, v129
	v_mov_b32_e32 v15, v129
	v_mov_b32_e32 v16, 0
	v_mov_b32_e32 v17, v129
	v_mov_b32_e32 v18, v129
	v_mov_b32_e32 v19, v129
	v_mov_b32_e32 v20, v129
	v_mov_b32_e32 v21, v129
	v_mov_b32_e32 v22, v129
	v_mov_b32_e32 v23, v129
	v_mov_b32_e32 v24, v129
	v_mov_b32_e32 v25, v129
	v_mov_b32_e32 v26, v129
	v_mov_b32_e32 v27, v129
	v_mov_b32_e32 v28, v129
	v_mov_b32_e32 v29, v129
	v_mov_b32_e32 v30, v129
	v_mov_b32_e32 v31, v129
	v_mov_b32_e32 v32, 0
	v_mov_b32_e32 v33, v129
	v_mov_b32_e32 v34, v129
	v_mov_b32_e32 v35, v129
	v_mov_b32_e32 v36, v129
	v_mov_b32_e32 v37, v129
	v_mov_b32_e32 v38, v129
	v_mov_b32_e32 v39, v129
	v_mov_b32_e32 v40, v129
	v_mov_b32_e32 v41, v129
	v_mov_b32_e32 v42, v129
	v_mov_b32_e32 v43, v129
	v_mov_b32_e32 v44, v129
	v_mov_b32_e32 v45, v129
	v_mov_b32_e32 v46, v129
	v_mov_b32_e32 v47, v129
	v_mov_b32_e32 v48, 0
	v_mov_b32_e32 v49, v129
	v_mov_b32_e32 v50, v129
	v_mov_b32_e32 v51, v129
	v_mov_b32_e32 v52, v129
	v_mov_b32_e32 v53, v129
	v_mov_b32_e32 v54, v129
	v_mov_b32_e32 v55, v129
	v_mov_b32_e32 v56, v129
	v_mov_b32_e32 v57, v129
	v_mov_b32_e32 v58, v129
	v_mov_b32_e32 v59, v129
	v_mov_b32_e32 v60, v129
	v_mov_b32_e32 v61, v129
	v_mov_b32_e32 v62, v129
	v_mov_b32_e32 v63, v129
	v_mov_b32_e32 v64, 0
	v_mov_b32_e32 v65, v129
	v_mov_b32_e32 v66, v129
	v_mov_b32_e32 v67, v129
	v_mov_b32_e32 v68, v129
	v_mov_b32_e32 v69, v129
	v_mov_b32_e32 v70, v129
	v_mov_b32_e32 v71, v129
	v_mov_b32_e32 v72, v129
	v_mov_b32_e32 v73, v129
	v_mov_b32_e32 v74, v129
	v_mov_b32_e32 v75, v129
	v_mov_b32_e32 v76, v129
	v_mov_b32_e32 v77, v129
	v_mov_b32_e32 v78, v129
	v_mov_b32_e32 v79, v129
	v_mov_b32_e32 v80, 0
	v_mov_b32_e32 v81, v129
	v_mov_b32_e32 v82, v129
	v_mov_b32_e32 v83, v129
	v_mov_b32_e32 v84, v129
	v_mov_b32_e32 v85, v129
	v_mov_b32_e32 v86, v129
	v_mov_b32_e32 v87, v129
	v_mov_b32_e32 v88, v129
	v_mov_b32_e32 v89, v129
	v_mov_b32_e32 v90, v129
	v_mov_b32_e32 v91, v129
	v_mov_b32_e32 v92, v129
	v_mov_b32_e32 v93, v129
	v_mov_b32_e32 v94, v129
	v_mov_b32_e32 v95, v129
	v_mov_b32_e32 v96, 0
	v_mov_b32_e32 v97, v129
	v_mov_b32_e32 v98, v129
	v_mov_b32_e32 v99, v129
	v_mov_b32_e32 v100, v129
	v_mov_b32_e32 v101, v129
	v_mov_b32_e32 v102, v129
	v_mov_b32_e32 v103, v129
	v_mov_b32_e32 v104, v129
	v_mov_b32_e32 v105, v129
	v_mov_b32_e32 v106, v129
	v_mov_b32_e32 v107, v129
	v_mov_b32_e32 v108, v129
	v_mov_b32_e32 v109, v129
	v_mov_b32_e32 v110, v129
	v_mov_b32_e32 v111, v129
	v_mov_b32_e32 v112, 0
	v_mov_b32_e32 v113, v129
	v_mov_b32_e32 v114, v129
	v_mov_b32_e32 v115, v129
	v_mov_b32_e32 v116, v129
	v_mov_b32_e32 v117, v129
	v_mov_b32_e32 v118, v129
	v_mov_b32_e32 v119, v129
	v_mov_b32_e32 v120, v129
	v_mov_b32_e32 v121, v129
	v_mov_b32_e32 v122, v129
	v_mov_b32_e32 v123, v129
	v_mov_b32_e32 v124, v129
	v_mov_b32_e32 v125, v129
	v_mov_b32_e32 v126, v129
	v_mov_b32_e32 v127, v129
	s_add_i32 s45, s44, 0x10000
	s_and_b32 s10, s45, 0x10000
	s_add_i32 s46, s10, s9
	s_add_i32 s47, s46, 0x8000
	s_add_u32 s10, s41, s0
	s_addc_u32 s11, s42, s1
	s_mov_b32 m0, s46
	global_load_lds_dwordx4 v145, s[10:11]
	s_add_u32 s10, s39, s0
	s_addc_u32 s11, s40, s1
	s_add_i32 s48, s46, 0x400
	s_mov_b32 m0, s48
	global_load_lds_dwordx4 v146, s[10:11]
	s_add_u32 s10, s37, s0
	s_addc_u32 s11, s38, s1
	s_add_i32 s48, s46, 0x800
	s_mov_b32 m0, s48
	global_load_lds_dwordx4 v145, s[10:11]
	s_add_u32 s10, s35, s0
	s_addc_u32 s11, s36, s1
	s_add_i32 s48, s46, 0xc00
	s_mov_b32 m0, s48
	global_load_lds_dwordx4 v146, s[10:11]
	s_add_u32 s10, s33, s0
	s_addc_u32 s11, s34, s1
	s_mov_b32 m0, s47
	global_load_lds_dwordx4 v145, s[10:11]
	s_add_u32 s10, s17, s0
	s_addc_u32 s11, s31, s1
	s_add_i32 s47, s46, 0x8400
	s_mov_b32 m0, s47
	global_load_lds_dwordx4 v146, s[10:11]
	s_add_u32 s10, s15, s0
	s_addc_u32 s11, s16, s1
	s_add_i32 s47, s46, 0x8800
	s_mov_b32 m0, s47
	global_load_lds_dwordx4 v145, s[10:11]
	s_add_u32 s10, s13, s0
	s_addc_u32 s11, s14, s1
	s_add_i32 s46, s46, 0x8c00
	s_mov_b32 m0, s46
	global_load_lds_dwordx4 v146, s[10:11]
	s_branch .LBB0_982

.LBB0_982:
	s_waitcnt vmcnt(0)
	s_barrier
	s_and_b32 s10, s44, 0x10000
	v_or_b32_e32 v128, s10, v148
	v_add_u32_e32 v142, v128, v149
	ds_read_b128 v[130:133], v142 offset:32768
	ds_read_b128 v[162:165], v142 offset:36864
	v_add_u32_e32 v143, s10, v147
	v_add_u32_e32 v153, v143, v149
	ds_read_b128 v[134:137], v153
	ds_read_b128 v[138:141], v153 offset:4096
	ds_read_b128 v[154:157], v153 offset:8192
	v_add_u32_e32 v142, v143, v150
	ds_read_b128 v[158:161], v153 offset:12288
	s_sub_u32 s101, s43, 1
	s_cmp_lt_u32 s101, 14
	s_mov_b64 s[10:11], -1
	s_cbranch_scc1 .LBB0_984
	s_add_i32 s45, s44, 0x10000
	s_mov_b64 s[10:11], 0

.LBB0_1053:
	s_lshl_b32 s0, s88, 3
	s_and_b32 s0, s0, 56
	s_bfe_u32 s1, s88, 0x30003
	s_or_b32 s28, s0, s1
	s_ashr_i32 s27, s88, 6
	s_lshl_b32 s0, s27, 8
	s_lshl_b32 s1, s28, 19
	s_add_u32 s18, s13, s1
	s_addc_u32 s19, s15, 0
	s_ashr_i32 s1, s0, 31
	s_lshl_b64 s[0:1], s[0:1], 11
	s_add_u32 s29, s20, s0
	v_readfirstlane_b32 s0, v152
	s_addc_u32 s30, s21, s1
	s_ashr_i32 s31, s0, 6
	s_lshl_b32 s0, s31, 5
	s_ashr_i32 s1, s0, 31
	s_lshl_b64 s[0:1], s[0:1], 11
	s_add_u32 s18, s18, s0
	s_addc_u32 s19, s19, s1
	s_add_u32 s0, s29, s0
	s_addc_u32 s1, s30, s1
	s_lshl_b32 s29, s31, 12
	s_add_i32 s33, s29, 0x8000
	s_add_u32 s30, s18, 0x4000
	s_barrier
	s_mov_b32 m0, s29
	global_load_lds_dwordx4 v153, s[18:19]
	s_addc_u32 s31, s19, 0
	s_or_b32 s34, s29, 0x400
	s_mov_b32 m0, s34
	global_load_lds_dwordx4 v154, s[30:31]
	s_add_u32 s30, s18, 0x8000
	s_addc_u32 s31, s19, 0
	s_or_b32 s34, s29, 0x800
	s_mov_b32 m0, s34
	global_load_lds_dwordx4 v153, s[30:31]
	s_add_u32 s30, s18, 0xc000
	s_addc_u32 s31, s19, 0
	s_or_b32 s34, s29, 0xc00
	s_mov_b32 m0, s34
	global_load_lds_dwordx4 v154, s[30:31]
	s_add_u32 s30, s0, 0x4000
	s_mov_b32 m0, s33
	global_load_lds_dwordx4 v153, s[0:1]
	s_addc_u32 s31, s1, 0
	s_add_i32 s33, s29, 0x8400
	s_mov_b32 m0, s33
	global_load_lds_dwordx4 v154, s[30:31]
	s_add_u32 s30, s0, 0x8000
	s_addc_u32 s31, s1, 0
	s_add_i32 s33, s29, 0x8800
	s_mov_b32 m0, s33
	global_load_lds_dwordx4 v153, s[30:31]
	s_add_u32 s30, s0, 0xc000
	s_addc_u32 s31, s1, 0
	s_add_i32 s33, s29, 0x8c00
	s_mov_b32 m0, s33
	global_load_lds_dwordx4 v154, s[30:31]
	s_add_u32 s30, s0, 0xc080
	s_addc_u32 s31, s1, 0
	s_add_u32 s33, s0, 0x8080
	s_addc_u32 s34, s1, 0
	s_add_u32 s35, s0, 0x4080
	s_addc_u32 s36, s1, 0
	s_add_u32 s37, s0, 0x80
	s_addc_u32 s38, s1, 0
	s_add_u32 s39, s18, 0xc080
	s_addc_u32 s40, s19, 0
	s_add_u32 s41, s18, 0x8080
	s_addc_u32 s42, s19, 0
	s_add_u32 s43, s18, 0x4080
	s_addc_u32 s44, s19, 0
	s_add_u32 s45, s18, 0x80
	s_addc_u32 s46, s19, 0
	s_mov_b64 s[0:1], 0
	s_mov_b32 s48, 0
	s_mov_b32 s47, 0
	s_waitcnt lgkmcnt(14)
	v_mov_b32_e32 v0, 0
	v_mov_b32_e32 v1, v145
	s_waitcnt lgkmcnt(13)
	v_mov_b32_e32 v2, v145
	s_waitcnt lgkmcnt(12)
	v_mov_b32_e32 v3, v145
	s_waitcnt lgkmcnt(11)
	v_mov_b32_e32 v4, v145
	s_waitcnt lgkmcnt(10)
	v_mov_b32_e32 v5, v145
	v_mov_b32_e32 v6, v145
	s_waitcnt lgkmcnt(9)
	v_mov_b32_e32 v7, v145
	s_waitcnt lgkmcnt(8)
	v_mov_b32_e32 v8, v145
	s_waitcnt lgkmcnt(7)
	v_mov_b32_e32 v9, v145
	s_waitcnt lgkmcnt(6)
	v_mov_b32_e32 v10, v145
	s_waitcnt lgkmcnt(5)
	v_mov_b32_e32 v11, v145
	s_waitcnt lgkmcnt(4)
	v_mov_b32_e32 v12, v145
	v_mov_b32_e32 v13, v145
	s_waitcnt lgkmcnt(3)
	v_mov_b32_e32 v14, v145
	s_waitcnt lgkmcnt(2)
	v_mov_b32_e32 v15, v145
	s_waitcnt lgkmcnt(1)
	v_mov_b32_e32 v16, 0
	v_mov_b32_e32 v17, v145
	v_mov_b32_e32 v18, v145
	v_mov_b32_e32 v19, v145
	v_mov_b32_e32 v20, v145
	v_mov_b32_e32 v21, v145
	v_mov_b32_e32 v22, v145
	v_mov_b32_e32 v23, v145
	v_mov_b32_e32 v24, v145
	v_mov_b32_e32 v25, v145
	v_mov_b32_e32 v26, v145
	v_mov_b32_e32 v27, v145
	v_mov_b32_e32 v28, v145
	v_mov_b32_e32 v29, v145
	v_mov_b32_e32 v30, v145
	v_mov_b32_e32 v31, v145
	v_mov_b32_e32 v32, 0
	v_mov_b32_e32 v33, v145
	v_mov_b32_e32 v34, v145
	v_mov_b32_e32 v35, v145
	v_mov_b32_e32 v36, v145
	v_mov_b32_e32 v37, v145
	v_mov_b32_e32 v38, v145
	v_mov_b32_e32 v39, v145
	v_mov_b32_e32 v40, v145
	v_mov_b32_e32 v41, v145
	v_mov_b32_e32 v42, v145
	v_mov_b32_e32 v43, v145
	v_mov_b32_e32 v44, v145
	v_mov_b32_e32 v45, v145
	v_mov_b32_e32 v46, v145
	s_waitcnt lgkmcnt(0)
	v_mov_b32_e32 v47, v145
	v_mov_b32_e32 v48, 0
	v_mov_b32_e32 v49, v145
	v_mov_b32_e32 v50, v145
	v_mov_b32_e32 v51, v145
	v_mov_b32_e32 v52, v145
	v_mov_b32_e32 v53, v145
	v_mov_b32_e32 v54, v145
	v_mov_b32_e32 v55, v145
	v_mov_b32_e32 v56, v145
	v_mov_b32_e32 v57, v145
	v_mov_b32_e32 v58, v145
	v_mov_b32_e32 v59, v145
	v_mov_b32_e32 v60, v145
	v_mov_b32_e32 v61, v145
	v_mov_b32_e32 v62, v145
	v_mov_b32_e32 v63, v145
	v_mov_b32_e32 v64, 0
	v_mov_b32_e32 v65, v145
	v_mov_b32_e32 v66, v145
	v_mov_b32_e32 v67, v145
	v_mov_b32_e32 v68, v145
	v_mov_b32_e32 v69, v145
	v_mov_b32_e32 v70, v145
	v_mov_b32_e32 v71, v145
	v_mov_b32_e32 v72, v145
	v_mov_b32_e32 v73, v145
	v_mov_b32_e32 v74, v145
	v_mov_b32_e32 v75, v145
	v_mov_b32_e32 v76, v145
	v_mov_b32_e32 v77, v145
	v_mov_b32_e32 v78, v145
	v_mov_b32_e32 v79, v145
	v_mov_b32_e32 v80, 0
	v_mov_b32_e32 v81, v145
	v_mov_b32_e32 v82, v145
	v_mov_b32_e32 v83, v145
	v_mov_b32_e32 v84, v145
	v_mov_b32_e32 v85, v145
	v_mov_b32_e32 v86, v145
	v_mov_b32_e32 v87, v145
	v_mov_b32_e32 v88, v145
	v_mov_b32_e32 v89, v145
	v_mov_b32_e32 v90, v145
	v_mov_b32_e32 v91, v145
	v_mov_b32_e32 v92, v145
	v_mov_b32_e32 v93, v145
	v_mov_b32_e32 v94, v145
	v_mov_b32_e32 v95, v145
	v_mov_b32_e32 v96, 0
	v_mov_b32_e32 v97, v145
	v_mov_b32_e32 v98, v145
	v_mov_b32_e32 v99, v145
	v_mov_b32_e32 v100, v145
	v_mov_b32_e32 v101, v145
	v_mov_b32_e32 v102, v145
	v_mov_b32_e32 v103, v145
	v_mov_b32_e32 v104, v145
	v_mov_b32_e32 v105, v145
	v_mov_b32_e32 v106, v145
	v_mov_b32_e32 v107, v145
	v_mov_b32_e32 v108, v145
	v_mov_b32_e32 v109, v145
	v_mov_b32_e32 v110, v145
	v_mov_b32_e32 v111, v145
	v_mov_b32_e32 v112, 0
	v_mov_b32_e32 v113, v145
	v_mov_b32_e32 v114, v145
	v_mov_b32_e32 v115, v145
	v_mov_b32_e32 v116, v145
	v_mov_b32_e32 v117, v145
	v_mov_b32_e32 v118, v145
	v_mov_b32_e32 v119, v145
	v_mov_b32_e32 v120, v145
	v_mov_b32_e32 v121, v145
	v_mov_b32_e32 v122, v145
	v_mov_b32_e32 v123, v145
	v_mov_b32_e32 v124, v145
	v_mov_b32_e32 v125, v145
	v_mov_b32_e32 v126, v145
	v_mov_b32_e32 v127, v145
	s_add_i32 s49, s48, 0x10000
	s_and_b32 s18, s49, 0x10000
	s_add_i32 s50, s18, s29
	s_add_i32 s51, s50, 0x8000
	s_add_u32 s18, s45, s0
	s_addc_u32 s19, s46, s1
	s_mov_b32 m0, s50
	global_load_lds_dwordx4 v153, s[18:19]
	s_add_u32 s18, s43, s0
	s_addc_u32 s19, s44, s1
	s_add_i32 s52, s50, 0x400
	s_mov_b32 m0, s52
	global_load_lds_dwordx4 v154, s[18:19]
	s_add_u32 s18, s41, s0
	s_addc_u32 s19, s42, s1
	s_add_i32 s52, s50, 0x800
	s_mov_b32 m0, s52
	global_load_lds_dwordx4 v153, s[18:19]
	s_add_u32 s18, s39, s0
	s_addc_u32 s19, s40, s1
	s_add_i32 s52, s50, 0xc00
	s_mov_b32 m0, s52
	global_load_lds_dwordx4 v154, s[18:19]
	s_add_u32 s18, s37, s0
	s_addc_u32 s19, s38, s1
	s_mov_b32 m0, s51
	global_load_lds_dwordx4 v153, s[18:19]
	s_add_u32 s18, s35, s0
	s_addc_u32 s19, s36, s1
	s_add_i32 s51, s50, 0x8400
	s_mov_b32 m0, s51
	global_load_lds_dwordx4 v154, s[18:19]
	s_add_u32 s18, s33, s0
	s_addc_u32 s19, s34, s1
	s_add_i32 s51, s50, 0x8800
	s_mov_b32 m0, s51
	global_load_lds_dwordx4 v153, s[18:19]
	s_add_u32 s18, s30, s0
	s_addc_u32 s19, s31, s1
	s_add_i32 s50, s50, 0x8c00
	s_mov_b32 m0, s50
	global_load_lds_dwordx4 v154, s[18:19]
	s_branch .LBB0_1055

.LBB0_1055:
	s_waitcnt vmcnt(0)
	s_barrier
	s_and_b32 s18, s48, 0x10000
	v_or_b32_e32 v144, s18, v156
	v_add_u32_e32 v150, v144, v157
	ds_read_b128 v[128:131], v150 offset:32768
	ds_read_b128 v[164:167], v150 offset:36864
	v_add_u32_e32 v151, s18, v155
	v_add_u32_e32 v146, v151, v157
	ds_read_b128 v[132:135], v146
	ds_read_b128 v[136:139], v146 offset:4096
	ds_read_b128 v[140:143], v146 offset:8192
	v_add_u32_e32 v150, v151, v158
	ds_read_b128 v[146:149], v146 offset:12288
	s_sub_u32 s101, s47, 1
	s_cmp_lt_u32 s101, 14
	s_mov_b64 s[18:19], -1
	s_cbranch_scc1 .LBB0_1057
	s_add_i32 s49, s48, 0x10000
	s_mov_b64 s[18:19], 0
